# residual epilogues: nt (streaming) hint on the residual loads and the f32 residual stores
# speedup vs baseline: 1.0031x; 1.0031x over previous
; __device__ __forceinline__ unsigned pk2(float lo, float hi) { const f32v2_t f = {lo, hi}; const bf16v2_t b = __builtin_convertvector(f, bf16v2_t); return __builtin_bit_cast(unsigned, b); }
;     __device__ __forceinline__ void operator()(const f32x4 (&acc)[2][2][4][2], const int upm, const int upn, const int usplit, int wr, int wc, int fr, int fq) const {
;     ...
;         const bool lat = upm * BM < NLAT; const int b = lat ? ((upm * BM) >> 11) : 16;
;         const float* gp = gate + (size_t)b * 6144 + col0;
;         f32x4 gv[2][2];
; #pragma unroll
;         for (int bj = 0; bj < 2; ++bj)
; #pragma unroll
;             for (int n = 0; n < 2; ++n) gv[bj][n] = *(const f32x4*)(gp + bj * HALF + n * 16);
;         const float* sb = lat ? src_lat : src_ctx - (size_t)NLAT * DM; float* db = lat ? dst_lat : dst_ctx - (size_t)NLAT * DM;
; #pragma unroll
;         for (int ai = 0; ai < 2; ++ai)
; #pragma unroll
;             for (int mh = 0; mh < 2; ++mh) {
;                 f32x4 xv[2][2][2];
; #pragma unroll
;                 for (int m = 0; m < 2; ++m)
; #pragma unroll
;                     for (int bj = 0; bj < 2; ++bj)
; #pragma unroll
;                         for (int n = 0; n < 2; ++n) xv[m][bj][n] = *(const f32x4*)(sb + (size_t)(row0 + ai * HALF + (mh * 2 + m) * 16) * DM + col0 + bj * HALF + n * 16);
;                 __builtin_amdgcn_sched_barrier(0);
; #pragma unroll
;                 for (int m = 0; m < 2; ++m)
; #pragma unroll
;                     for (int bj = 0; bj < 2; ++bj)
; #pragma unroll
;                         for (int n = 0; n < 2; ++n) {
;                             const size_t o = (size_t)(row0 + ai * HALF + (mh * 2 + m) * 16) * DM + col0 + bj * HALF + n * 16;
;                             const f32x4 r = xv[m][bj][n] + gv[bj][n] * acc[ai][bj][mh * 2 + m][n];
;                             *(f32x4*)(db + o) = r;
;                             if (xb && lat) { u32x2 pk; pk.x = pk2(r[0], r[1]); pk.y = pk2(r[2], r[3]); *(u32x2*)(xb + o) = pk; }
;                         }
.LBB0_1497:
	s_lshl_b64 s[30:31], s[90:91], 2
	s_add_u32 s30, s22, s30
	s_addc_u32 s31, s23, s31
	v_mbcnt_lo_u32_b32 v152, -1, 0
	v_mbcnt_hi_u32_b32 v152, -1, v152
	v_and_b32_e32 v153, 15, v152
	v_lshrrev_b32_e32 v154, 2, v152
	v_lshrrev_b32_e32 v155, 4, v152
	v_and_b32_e32 v156, 3, v152
	v_sub_u32_e32 v192, v192, v153
	v_add_u32_e32 v192, v192, v154
	v_ashrrev_i32_e32 v193, 31, v192
	v_sub_u32_e32 v157, v156, v155
	v_lshl_add_u32 v190, v157, 2, v190
	v_ashrrev_i32_e32 v191, 31, v190
	v_lshl_add_u32 v158, v156, 4, v154
	v_lshlrev_b64 v[198:199], 2, v[190:191]
	v_lshl_add_u64 v[242:243], s[30:31], 0, v[198:199]
	v_lshl_add_u64 v[200:201], s[74:75], 0, v[198:199]
	v_lshl_add_u64 v[218:219], s[68:69], 0, v[198:199]
	v_lshlrev_b64 v[198:199], 12, v[192:193]
	v_lshl_add_u64 v[200:201], v[200:201], 0, v[198:199]
	v_lshl_add_u64 v[218:219], v[218:219], 0, v[198:199]
	global_load_dwordx4 v[148:151], v[242:243], off
	global_load_dwordx4 v[144:147], v[242:243], off offset:64
	global_load_dwordx4 v[140:143], v[242:243], off offset:512
	global_load_dwordx4 v[136:139], v[242:243], off offset:576
	v_lshlrev_b64 v[198:199], 1, v[190:191]
	v_lshl_add_u64 v[242:243], s[44:45], 0, v[198:199]
	v_lshlrev_b64 v[198:199], 11, v[192:193]
	v_lshl_add_u64 v[242:243], v[242:243], 0, v[198:199]
	v_lshlrev_b32_e32 v198, 2, v158
	global_load_dwordx4 v[152:155], v[200:201], off nt
	global_load_dwordx4 v[156:159], v[200:201], off offset:64 nt
	global_load_dwordx4 v[160:163], v[200:201], off offset:512 nt
	global_load_dwordx4 v[164:167], v[200:201], off offset:576 nt
	s_mov_b32 s30, 0x10000
	s_mov_b32 s31, 0
	v_lshl_add_u64 v[200:201], v[200:201], 0, s[30:31]
	global_load_dwordx4 v[168:171], v[200:201], off nt
	global_load_dwordx4 v[172:175], v[200:201], off offset:64 nt
	global_load_dwordx4 v[176:179], v[200:201], off offset:512 nt
	global_load_dwordx4 v[180:183], v[200:201], off offset:576 nt
	s_mov_b32 s30, 0x10000
	s_mov_b32 s31, 0
	v_lshl_add_u64 v[200:201], v[200:201], 0, s[30:31]
	global_load_dwordx4 v[190:193], v[200:201], off nt
	global_load_dwordx4 v[194:197], v[200:201], off offset:64 nt
	global_load_dwordx4 v[234:237], v[200:201], off offset:512 nt
	global_load_dwordx4 v[238:241], v[200:201], off offset:576 nt
	s_mov_b32 s30, 0x10000
	s_mov_b32 s31, 0
	v_lshl_add_u64 v[200:201], v[200:201], 0, s[30:31]
	s_and_b64 s[30:31], s[58:59], s[72:73]
	s_xor_b64 s[66:67], s[30:31], -1
	s_and_b64 vcc, exec, s[66:67]
	s_cbranch_vccnz .Lmy_epi_p4_nobf
	ds_bpermute_b32 v132, v198, v132
	ds_bpermute_b32 v133, v198, v133
	ds_bpermute_b32 v134, v198, v134
	ds_bpermute_b32 v135, v198, v135
	ds_bpermute_b32 v128, v198, v128
	ds_bpermute_b32 v129, v198, v129
	ds_bpermute_b32 v130, v198, v130
	ds_bpermute_b32 v131, v198, v131
	ds_bpermute_b32 v124, v198, v124
	ds_bpermute_b32 v125, v198, v125
	ds_bpermute_b32 v126, v198, v126
	ds_bpermute_b32 v127, v198, v127
	ds_bpermute_b32 v120, v198, v120
	ds_bpermute_b32 v121, v198, v121
	ds_bpermute_b32 v122, v198, v122
	ds_bpermute_b32 v123, v198, v123
	s_waitcnt vmcnt(8)
	s_waitcnt lgkmcnt(0)
	v_pk_fma_f32 v[152:153], v[132:133], v[148:149], v[152:153]
	v_pk_fma_f32 v[154:155], v[134:135], v[150:151], v[154:155]
	v_pk_fma_f32 v[156:157], v[128:129], v[144:145], v[156:157]
	v_pk_fma_f32 v[158:159], v[130:131], v[146:147], v[158:159]
	v_pk_fma_f32 v[160:161], v[124:125], v[140:141], v[160:161]
	v_pk_fma_f32 v[162:163], v[126:127], v[142:143], v[162:163]
	v_pk_fma_f32 v[164:165], v[120:121], v[136:137], v[164:165]
	v_pk_fma_f32 v[166:167], v[122:123], v[138:139], v[166:167]
	global_store_dwordx4 v[218:219], v[152:155], off nt
	global_store_dwordx4 v[218:219], v[156:159], off offset:64 nt
	global_store_dwordx4 v[218:219], v[160:163], off offset:512 nt
	global_store_dwordx4 v[218:219], v[164:167], off offset:576 nt
	v_cvt_pk_bf16_f32 v132, v152, v153
	v_cvt_pk_bf16_f32 v133, v154, v155
	v_cvt_pk_bf16_f32 v128, v156, v157
	v_cvt_pk_bf16_f32 v129, v158, v159
	v_cvt_pk_bf16_f32 v124, v160, v161
	v_cvt_pk_bf16_f32 v125, v162, v163
	v_cvt_pk_bf16_f32 v120, v164, v165
	v_cvt_pk_bf16_f32 v121, v166, v167
	global_store_dwordx2 v[242:243], v[132:133], off
	global_store_dwordx2 v[242:243], v[128:129], off offset:32
	global_store_dwordx2 v[242:243], v[124:125], off offset:256
	global_store_dwordx2 v[242:243], v[120:121], off offset:288
	s_mov_b32 s30, 0x10000
	s_mov_b32 s31, 0
	v_lshl_add_u64 v[218:219], v[218:219], 0, s[30:31]
	s_mov_b32 s30, 0x8000
	s_mov_b32 s31, 0
	v_lshl_add_u64 v[242:243], v[242:243], 0, s[30:31]
	global_load_dwordx4 v[152:155], v[200:201], off nt
	global_load_dwordx4 v[156:159], v[200:201], off offset:64 nt
	global_load_dwordx4 v[160:163], v[200:201], off offset:512 nt
	global_load_dwordx4 v[164:167], v[200:201], off offset:576 nt
	s_mov_b32 s30, 0x50000
	s_mov_b32 s31, 0
	v_lshl_add_u64 v[200:201], v[200:201], 0, s[30:31]
	global_load_dwordx4 v[132:135], v[200:201], off nt
	global_load_dwordx4 v[128:131], v[200:201], off offset:64 nt
	global_load_dwordx4 v[124:127], v[200:201], off offset:512 nt
	global_load_dwordx4 v[120:123], v[200:201], off offset:576 nt
	s_mov_b32 s30, 0x10000
	s_mov_b32 s31, 0
	v_lshl_add_u64 v[200:201], v[200:201], 0, s[30:31]
	ds_bpermute_b32 v116, v198, v116
	ds_bpermute_b32 v117, v198, v117
	ds_bpermute_b32 v118, v198, v118
	ds_bpermute_b32 v119, v198, v119
	ds_bpermute_b32 v112, v198, v112
	ds_bpermute_b32 v113, v198, v113
	ds_bpermute_b32 v114, v198, v114
	ds_bpermute_b32 v115, v198, v115
	ds_bpermute_b32 v108, v198, v108
	ds_bpermute_b32 v109, v198, v109
	ds_bpermute_b32 v110, v198, v110
	ds_bpermute_b32 v111, v198, v111
	ds_bpermute_b32 v104, v198, v104
	ds_bpermute_b32 v105, v198, v105
	ds_bpermute_b32 v106, v198, v106
	ds_bpermute_b32 v107, v198, v107
	s_waitcnt vmcnt(20)
; __device__ __forceinline__ unsigned pk2(float lo, float hi) { const f32v2_t f = {lo, hi}; const bf16v2_t b = __builtin_convertvector(f, bf16v2_t); return __builtin_bit_cast(unsigned, b); }
;     __device__ __forceinline__ void operator()(const f32x4 (&acc)[2][2][4][2], const int upm, const int upn, const int usplit, int wr, int wc, int fr, int fq) const {
;     ...
; #pragma unroll
;                 for (int m = 0; m < 2; ++m)
; #pragma unroll
;                     for (int bj = 0; bj < 2; ++bj)
; #pragma unroll
;                         for (int n = 0; n < 2; ++n) {
;                             const size_t o = (size_t)(row0 + ai * HALF + (mh * 2 + m) * 16) * DM + col0 + bj * HALF + n * 16;
;                             const f32x4 r = xv[m][bj][n] + gv[bj][n] * acc[ai][bj][mh * 2 + m][n];
;                             *(f32x4*)(db + o) = r;
;                             if (xb && lat) { u32x2 pk; pk.x = pk2(r[0], r[1]); pk.y = pk2(r[2], r[3]); *(u32x2*)(xb + o) = pk; }
;                         }
	s_waitcnt lgkmcnt(0)
	v_pk_fma_f32 v[168:169], v[116:117], v[148:149], v[168:169]
	v_pk_fma_f32 v[170:171], v[118:119], v[150:151], v[170:171]
	v_pk_fma_f32 v[172:173], v[112:113], v[144:145], v[172:173]
	v_pk_fma_f32 v[174:175], v[114:115], v[146:147], v[174:175]
	v_pk_fma_f32 v[176:177], v[108:109], v[140:141], v[176:177]
	v_pk_fma_f32 v[178:179], v[110:111], v[142:143], v[178:179]
	v_pk_fma_f32 v[180:181], v[104:105], v[136:137], v[180:181]
	v_pk_fma_f32 v[182:183], v[106:107], v[138:139], v[182:183]
	global_store_dwordx4 v[218:219], v[168:171], off nt
	global_store_dwordx4 v[218:219], v[172:175], off offset:64 nt
	global_store_dwordx4 v[218:219], v[176:179], off offset:512 nt
	global_store_dwordx4 v[218:219], v[180:183], off offset:576 nt
	v_cvt_pk_bf16_f32 v116, v168, v169
	v_cvt_pk_bf16_f32 v117, v170, v171
	v_cvt_pk_bf16_f32 v112, v172, v173
	v_cvt_pk_bf16_f32 v113, v174, v175
	v_cvt_pk_bf16_f32 v108, v176, v177
	v_cvt_pk_bf16_f32 v109, v178, v179
	v_cvt_pk_bf16_f32 v104, v180, v181
	v_cvt_pk_bf16_f32 v105, v182, v183
	global_store_dwordx2 v[242:243], v[116:117], off
	global_store_dwordx2 v[242:243], v[112:113], off offset:32
	global_store_dwordx2 v[242:243], v[108:109], off offset:256
	global_store_dwordx2 v[242:243], v[104:105], off offset:288
	s_mov_b32 s30, 0x10000
	s_mov_b32 s31, 0
	v_lshl_add_u64 v[218:219], v[218:219], 0, s[30:31]
	s_mov_b32 s30, 0x8000
	s_mov_b32 s31, 0
	v_lshl_add_u64 v[242:243], v[242:243], 0, s[30:31]
	global_load_dwordx4 v[168:171], v[200:201], off nt
	global_load_dwordx4 v[172:175], v[200:201], off offset:64 nt
	global_load_dwordx4 v[176:179], v[200:201], off offset:512 nt
	global_load_dwordx4 v[180:183], v[200:201], off offset:576 nt
	s_mov_b32 s30, 0x10000
	s_mov_b32 s31, 0
	v_lshl_add_u64 v[200:201], v[200:201], 0, s[30:31]
	global_load_dwordx4 v[116:119], v[200:201], off nt
	global_load_dwordx4 v[112:115], v[200:201], off offset:64 nt
	global_load_dwordx4 v[108:111], v[200:201], off offset:512 nt
	global_load_dwordx4 v[104:107], v[200:201], off offset:576 nt
	s_mov_b32 s30, 0x10000
	s_mov_b32 s31, 0
	v_lshl_add_u64 v[200:201], v[200:201], 0, s[30:31]
	ds_bpermute_b32 v100, v198, v100
	ds_bpermute_b32 v101, v198, v101
	ds_bpermute_b32 v102, v198, v102
	ds_bpermute_b32 v103, v198, v103
	ds_bpermute_b32 v96, v198, v96
	ds_bpermute_b32 v97, v198, v97
	ds_bpermute_b32 v98, v198, v98
	ds_bpermute_b32 v99, v198, v99
	ds_bpermute_b32 v92, v198, v92
	ds_bpermute_b32 v93, v198, v93
	ds_bpermute_b32 v94, v198, v94
	ds_bpermute_b32 v95, v198, v95
	ds_bpermute_b32 v88, v198, v88
	ds_bpermute_b32 v89, v198, v89
	ds_bpermute_b32 v90, v198, v90
	ds_bpermute_b32 v91, v198, v91
	s_waitcnt vmcnt(32)
	s_waitcnt lgkmcnt(0)
	v_pk_fma_f32 v[190:191], v[100:101], v[148:149], v[190:191]
	v_pk_fma_f32 v[192:193], v[102:103], v[150:151], v[192:193]
	v_pk_fma_f32 v[194:195], v[96:97], v[144:145], v[194:195]
	v_pk_fma_f32 v[196:197], v[98:99], v[146:147], v[196:197]
	v_pk_fma_f32 v[234:235], v[92:93], v[140:141], v[234:235]
	v_pk_fma_f32 v[236:237], v[94:95], v[142:143], v[236:237]
	v_pk_fma_f32 v[238:239], v[88:89], v[136:137], v[238:239]
	v_pk_fma_f32 v[240:241], v[90:91], v[138:139], v[240:241]
	global_store_dwordx4 v[218:219], v[190:193], off nt
	global_store_dwordx4 v[218:219], v[194:197], off offset:64 nt
	global_store_dwordx4 v[218:219], v[234:237], off offset:512 nt
	global_store_dwordx4 v[218:219], v[238:241], off offset:576 nt
	v_cvt_pk_bf16_f32 v100, v190, v191
	v_cvt_pk_bf16_f32 v101, v192, v193
	v_cvt_pk_bf16_f32 v96, v194, v195
	v_cvt_pk_bf16_f32 v97, v196, v197
	v_cvt_pk_bf16_f32 v92, v234, v235
	v_cvt_pk_bf16_f32 v93, v236, v237
	v_cvt_pk_bf16_f32 v88, v238, v239
	v_cvt_pk_bf16_f32 v89, v240, v241
	global_store_dwordx2 v[242:243], v[100:101], off
	global_store_dwordx2 v[242:243], v[96:97], off offset:32
	global_store_dwordx2 v[242:243], v[92:93], off offset:256
	global_store_dwordx2 v[242:243], v[88:89], off offset:288
	s_mov_b32 s30, 0x10000
	s_mov_b32 s31, 0
	v_lshl_add_u64 v[218:219], v[218:219], 0, s[30:31]
	s_mov_b32 s30, 0x8000
	s_mov_b32 s31, 0
	v_lshl_add_u64 v[242:243], v[242:243], 0, s[30:31]
	global_load_dwordx4 v[190:193], v[200:201], off nt
	global_load_dwordx4 v[194:197], v[200:201], off offset:64 nt
	global_load_dwordx4 v[234:237], v[200:201], off offset:512 nt
	global_load_dwordx4 v[238:241], v[200:201], off offset:576 nt
	ds_bpermute_b32 v84, v198, v84
	ds_bpermute_b32 v85, v198, v85
	ds_bpermute_b32 v86, v198, v86
	ds_bpermute_b32 v87, v198, v87
	ds_bpermute_b32 v80, v198, v80
	ds_bpermute_b32 v81, v198, v81
	ds_bpermute_b32 v82, v198, v82
	ds_bpermute_b32 v83, v198, v83
	ds_bpermute_b32 v76, v198, v76
	ds_bpermute_b32 v77, v198, v77
	ds_bpermute_b32 v78, v198, v78
	ds_bpermute_b32 v79, v198, v79
	ds_bpermute_b32 v72, v198, v72
	ds_bpermute_b32 v73, v198, v73
	ds_bpermute_b32 v74, v198, v74
	ds_bpermute_b32 v75, v198, v75
	s_waitcnt vmcnt(32)
	s_waitcnt lgkmcnt(0)
; __device__ __forceinline__ unsigned pk2(float lo, float hi) { const f32v2_t f = {lo, hi}; const bf16v2_t b = __builtin_convertvector(f, bf16v2_t); return __builtin_bit_cast(unsigned, b); }
;     __device__ __forceinline__ void operator()(const f32x4 (&acc)[2][2][4][2], const int upm, const int upn, const int usplit, int wr, int wc, int fr, int fq) const {
;     ...
; #pragma unroll
;         for (int ai = 0; ai < 2; ++ai)
; #pragma unroll
;             for (int mh = 0; mh < 2; ++mh) {
;                 f32x4 xv[2][2][2];
; #pragma unroll
;                 for (int m = 0; m < 2; ++m)
; #pragma unroll
;                     for (int bj = 0; bj < 2; ++bj)
; #pragma unroll
;                         for (int n = 0; n < 2; ++n) xv[m][bj][n] = *(const f32x4*)(sb + (size_t)(row0 + ai * HALF + (mh * 2 + m) * 16) * DM + col0 + bj * HALF + n * 16);
;                 __builtin_amdgcn_sched_barrier(0);
; #pragma unroll
;                 for (int m = 0; m < 2; ++m)
; #pragma unroll
;                     for (int bj = 0; bj < 2; ++bj)
; #pragma unroll
;                         for (int n = 0; n < 2; ++n) {
;                             const size_t o = (size_t)(row0 + ai * HALF + (mh * 2 + m) * 16) * DM + col0 + bj * HALF + n * 16;
;                             const f32x4 r = xv[m][bj][n] + gv[bj][n] * acc[ai][bj][mh * 2 + m][n];
;                             *(f32x4*)(db + o) = r;
;                             if (xb && lat) { u32x2 pk; pk.x = pk2(r[0], r[1]); pk.y = pk2(r[2], r[3]); *(u32x2*)(xb + o) = pk; }
;                         }
	v_pk_fma_f32 v[152:153], v[84:85], v[148:149], v[152:153]
	v_pk_fma_f32 v[154:155], v[86:87], v[150:151], v[154:155]
	v_pk_fma_f32 v[156:157], v[80:81], v[144:145], v[156:157]
	v_pk_fma_f32 v[158:159], v[82:83], v[146:147], v[158:159]
	v_pk_fma_f32 v[160:161], v[76:77], v[140:141], v[160:161]
	v_pk_fma_f32 v[162:163], v[78:79], v[142:143], v[162:163]
	v_pk_fma_f32 v[164:165], v[72:73], v[136:137], v[164:165]
	v_pk_fma_f32 v[166:167], v[74:75], v[138:139], v[166:167]
	global_store_dwordx4 v[218:219], v[152:155], off nt
	global_store_dwordx4 v[218:219], v[156:159], off offset:64 nt
	global_store_dwordx4 v[218:219], v[160:163], off offset:512 nt
	global_store_dwordx4 v[218:219], v[164:167], off offset:576 nt
	v_cvt_pk_bf16_f32 v84, v152, v153
	v_cvt_pk_bf16_f32 v85, v154, v155
	v_cvt_pk_bf16_f32 v80, v156, v157
	v_cvt_pk_bf16_f32 v81, v158, v159
	v_cvt_pk_bf16_f32 v76, v160, v161
	v_cvt_pk_bf16_f32 v77, v162, v163
	v_cvt_pk_bf16_f32 v72, v164, v165
	v_cvt_pk_bf16_f32 v73, v166, v167
	global_store_dwordx2 v[242:243], v[84:85], off
	global_store_dwordx2 v[242:243], v[80:81], off offset:32
	global_store_dwordx2 v[242:243], v[76:77], off offset:256
	global_store_dwordx2 v[242:243], v[72:73], off offset:288
	s_mov_b32 s30, 0x50000
	s_mov_b32 s31, 0
	v_lshl_add_u64 v[218:219], v[218:219], 0, s[30:31]
	s_mov_b32 s30, 0x28000
	s_mov_b32 s31, 0
	v_lshl_add_u64 v[242:243], v[242:243], 0, s[30:31]
	ds_bpermute_b32 v68, v198, v68
	ds_bpermute_b32 v69, v198, v69
	ds_bpermute_b32 v70, v198, v70
	ds_bpermute_b32 v71, v198, v71
	ds_bpermute_b32 v64, v198, v64
	ds_bpermute_b32 v65, v198, v65
	ds_bpermute_b32 v66, v198, v66
	ds_bpermute_b32 v67, v198, v67
	ds_bpermute_b32 v60, v198, v60
	ds_bpermute_b32 v61, v198, v61
	ds_bpermute_b32 v62, v198, v62
	ds_bpermute_b32 v63, v198, v63
	ds_bpermute_b32 v56, v198, v56
	ds_bpermute_b32 v57, v198, v57
	ds_bpermute_b32 v58, v198, v58
	ds_bpermute_b32 v59, v198, v59
	s_waitcnt vmcnt(36)
	s_waitcnt lgkmcnt(0)
	v_pk_fma_f32 v[132:133], v[68:69], v[148:149], v[132:133]
	v_pk_fma_f32 v[134:135], v[70:71], v[150:151], v[134:135]
	v_pk_fma_f32 v[128:129], v[64:65], v[144:145], v[128:129]
	v_pk_fma_f32 v[130:131], v[66:67], v[146:147], v[130:131]
	v_pk_fma_f32 v[124:125], v[60:61], v[140:141], v[124:125]
	v_pk_fma_f32 v[126:127], v[62:63], v[142:143], v[126:127]
	v_pk_fma_f32 v[120:121], v[56:57], v[136:137], v[120:121]
	v_pk_fma_f32 v[122:123], v[58:59], v[138:139], v[122:123]
	global_store_dwordx4 v[218:219], v[132:135], off nt
	global_store_dwordx4 v[218:219], v[128:131], off offset:64 nt
	global_store_dwordx4 v[218:219], v[124:127], off offset:512 nt
	global_store_dwordx4 v[218:219], v[120:123], off offset:576 nt
	v_cvt_pk_bf16_f32 v68, v132, v133
	v_cvt_pk_bf16_f32 v69, v134, v135
	v_cvt_pk_bf16_f32 v64, v128, v129
	v_cvt_pk_bf16_f32 v65, v130, v131
	v_cvt_pk_bf16_f32 v60, v124, v125
	v_cvt_pk_bf16_f32 v61, v126, v127
	v_cvt_pk_bf16_f32 v56, v120, v121
	v_cvt_pk_bf16_f32 v57, v122, v123
	global_store_dwordx2 v[242:243], v[68:69], off
	global_store_dwordx2 v[242:243], v[64:65], off offset:32
	global_store_dwordx2 v[242:243], v[60:61], off offset:256
	global_store_dwordx2 v[242:243], v[56:57], off offset:288
	s_mov_b32 s30, 0x10000
	s_mov_b32 s31, 0
	v_lshl_add_u64 v[218:219], v[218:219], 0, s[30:31]
	s_mov_b32 s30, 0x8000
	s_mov_b32 s31, 0
	v_lshl_add_u64 v[242:243], v[242:243], 0, s[30:31]
	ds_bpermute_b32 v52, v198, v52
	ds_bpermute_b32 v53, v198, v53
	ds_bpermute_b32 v54, v198, v54
	ds_bpermute_b32 v55, v198, v55
	ds_bpermute_b32 v48, v198, v48
	ds_bpermute_b32 v49, v198, v49
	ds_bpermute_b32 v50, v198, v50
	ds_bpermute_b32 v51, v198, v51
	ds_bpermute_b32 v44, v198, v44
	ds_bpermute_b32 v45, v198, v45
	ds_bpermute_b32 v46, v198, v46
	ds_bpermute_b32 v47, v198, v47
	ds_bpermute_b32 v40, v198, v40
	ds_bpermute_b32 v41, v198, v41
	ds_bpermute_b32 v42, v198, v42
	ds_bpermute_b32 v43, v198, v43
	s_waitcnt vmcnt(32)
	s_waitcnt lgkmcnt(0)
	v_pk_fma_f32 v[168:169], v[52:53], v[148:149], v[168:169]
	v_pk_fma_f32 v[170:171], v[54:55], v[150:151], v[170:171]
	v_pk_fma_f32 v[172:173], v[48:49], v[144:145], v[172:173]
	v_pk_fma_f32 v[174:175], v[50:51], v[146:147], v[174:175]
	v_pk_fma_f32 v[176:177], v[44:45], v[140:141], v[176:177]
	v_pk_fma_f32 v[178:179], v[46:47], v[142:143], v[178:179]
	v_pk_fma_f32 v[180:181], v[40:41], v[136:137], v[180:181]
	v_pk_fma_f32 v[182:183], v[42:43], v[138:139], v[182:183]
	global_store_dwordx4 v[218:219], v[168:171], off nt
	global_store_dwordx4 v[218:219], v[172:175], off offset:64 nt
	global_store_dwordx4 v[218:219], v[176:179], off offset:512 nt
	global_store_dwordx4 v[218:219], v[180:183], off offset:576 nt
	v_cvt_pk_bf16_f32 v52, v168, v169
	v_cvt_pk_bf16_f32 v53, v170, v171
	v_cvt_pk_bf16_f32 v48, v172, v173
	v_cvt_pk_bf16_f32 v49, v174, v175
	v_cvt_pk_bf16_f32 v44, v176, v177
	v_cvt_pk_bf16_f32 v45, v178, v179
	v_cvt_pk_bf16_f32 v40, v180, v181
	v_cvt_pk_bf16_f32 v41, v182, v183
	global_store_dwordx2 v[242:243], v[52:53], off
	global_store_dwordx2 v[242:243], v[48:49], off offset:32
	global_store_dwordx2 v[242:243], v[44:45], off offset:256
	global_store_dwordx2 v[242:243], v[40:41], off offset:288
	s_mov_b32 s30, 0x10000
	s_mov_b32 s31, 0
	v_lshl_add_u64 v[218:219], v[218:219], 0, s[30:31]
	s_mov_b32 s30, 0x8000
	s_mov_b32 s31, 0
	v_lshl_add_u64 v[242:243], v[242:243], 0, s[30:31]
	ds_bpermute_b32 v36, v198, v36
	ds_bpermute_b32 v37, v198, v37
	ds_bpermute_b32 v38, v198, v38
	ds_bpermute_b32 v39, v198, v39
	ds_bpermute_b32 v32, v198, v32
	ds_bpermute_b32 v33, v198, v33
	ds_bpermute_b32 v34, v198, v34
	ds_bpermute_b32 v35, v198, v35
	ds_bpermute_b32 v28, v198, v28
	ds_bpermute_b32 v29, v198, v29
	ds_bpermute_b32 v30, v198, v30
	ds_bpermute_b32 v31, v198, v31
	ds_bpermute_b32 v24, v198, v24
	ds_bpermute_b32 v25, v198, v25
	ds_bpermute_b32 v26, v198, v26
	ds_bpermute_b32 v27, v198, v27
	s_waitcnt vmcnt(36)
; __device__ __forceinline__ unsigned pk2(float lo, float hi) { const f32v2_t f = {lo, hi}; const bf16v2_t b = __builtin_convertvector(f, bf16v2_t); return __builtin_bit_cast(unsigned, b); }
;     __device__ __forceinline__ void operator()(const f32x4 (&acc)[2][2][4][2], const int upm, const int upn, const int usplit, int wr, int wc, int fr, int fq) const {
;     ...
; #pragma unroll
;         for (int ai = 0; ai < 2; ++ai)
; #pragma unroll
;             for (int mh = 0; mh < 2; ++mh) {
;                 f32x4 xv[2][2][2];
; #pragma unroll
;                 for (int m = 0; m < 2; ++m)
; #pragma unroll
;                     for (int bj = 0; bj < 2; ++bj)
; #pragma unroll
;                         for (int n = 0; n < 2; ++n) xv[m][bj][n] = *(const f32x4*)(sb + (size_t)(row0 + ai * HALF + (mh * 2 + m) * 16) * DM + col0 + bj * HALF + n * 16);
;                 __builtin_amdgcn_sched_barrier(0);
; #pragma unroll
;                 for (int m = 0; m < 2; ++m)
; #pragma unroll
;                     for (int bj = 0; bj < 2; ++bj)
; #pragma unroll
;                         for (int n = 0; n < 2; ++n) {
;                             const size_t o = (size_t)(row0 + ai * HALF + (mh * 2 + m) * 16) * DM + col0 + bj * HALF + n * 16;
;                             const f32x4 r = xv[m][bj][n] + gv[bj][n] * acc[ai][bj][mh * 2 + m][n];
;                             *(f32x4*)(db + o) = r;
;                             if (xb && lat) { u32x2 pk; pk.x = pk2(r[0], r[1]); pk.y = pk2(r[2], r[3]); *(u32x2*)(xb + o) = pk; }
;                         }
	s_waitcnt lgkmcnt(0)
	v_pk_fma_f32 v[116:117], v[36:37], v[148:149], v[116:117]
	v_pk_fma_f32 v[118:119], v[38:39], v[150:151], v[118:119]
	v_pk_fma_f32 v[112:113], v[32:33], v[144:145], v[112:113]
	v_pk_fma_f32 v[114:115], v[34:35], v[146:147], v[114:115]
	v_pk_fma_f32 v[108:109], v[28:29], v[140:141], v[108:109]
	v_pk_fma_f32 v[110:111], v[30:31], v[142:143], v[110:111]
	v_pk_fma_f32 v[104:105], v[24:25], v[136:137], v[104:105]
	v_pk_fma_f32 v[106:107], v[26:27], v[138:139], v[106:107]
	global_store_dwordx4 v[218:219], v[116:119], off nt
	global_store_dwordx4 v[218:219], v[112:115], off offset:64 nt
	global_store_dwordx4 v[218:219], v[108:111], off offset:512 nt
	global_store_dwordx4 v[218:219], v[104:107], off offset:576 nt
	v_cvt_pk_bf16_f32 v36, v116, v117
	v_cvt_pk_bf16_f32 v37, v118, v119
	v_cvt_pk_bf16_f32 v32, v112, v113
	v_cvt_pk_bf16_f32 v33, v114, v115
	v_cvt_pk_bf16_f32 v28, v108, v109
	v_cvt_pk_bf16_f32 v29, v110, v111
	v_cvt_pk_bf16_f32 v24, v104, v105
	v_cvt_pk_bf16_f32 v25, v106, v107
	global_store_dwordx2 v[242:243], v[36:37], off
	global_store_dwordx2 v[242:243], v[32:33], off offset:32
	global_store_dwordx2 v[242:243], v[28:29], off offset:256
	global_store_dwordx2 v[242:243], v[24:25], off offset:288
	s_mov_b32 s30, 0x10000
	s_mov_b32 s31, 0
	v_lshl_add_u64 v[218:219], v[218:219], 0, s[30:31]
	s_mov_b32 s30, 0x8000
	s_mov_b32 s31, 0
	v_lshl_add_u64 v[242:243], v[242:243], 0, s[30:31]
	ds_bpermute_b32 v20, v198, v20
	ds_bpermute_b32 v21, v198, v21
	ds_bpermute_b32 v22, v198, v22
	ds_bpermute_b32 v23, v198, v23
	ds_bpermute_b32 v16, v198, v16
	ds_bpermute_b32 v17, v198, v17
	ds_bpermute_b32 v18, v198, v18
	ds_bpermute_b32 v19, v198, v19
	ds_bpermute_b32 v12, v198, v12
	ds_bpermute_b32 v13, v198, v13
	ds_bpermute_b32 v14, v198, v14
	ds_bpermute_b32 v15, v198, v15
	ds_bpermute_b32 v8, v198, v8
	ds_bpermute_b32 v9, v198, v9
	ds_bpermute_b32 v10, v198, v10
	ds_bpermute_b32 v11, v198, v11
	s_waitcnt vmcnt(32)
	s_waitcnt lgkmcnt(0)
	v_pk_fma_f32 v[190:191], v[20:21], v[148:149], v[190:191]
	v_pk_fma_f32 v[192:193], v[22:23], v[150:151], v[192:193]
	v_pk_fma_f32 v[194:195], v[16:17], v[144:145], v[194:195]
	v_pk_fma_f32 v[196:197], v[18:19], v[146:147], v[196:197]
	v_pk_fma_f32 v[234:235], v[12:13], v[140:141], v[234:235]
	v_pk_fma_f32 v[236:237], v[14:15], v[142:143], v[236:237]
	v_pk_fma_f32 v[238:239], v[8:9], v[136:137], v[238:239]
	v_pk_fma_f32 v[240:241], v[10:11], v[138:139], v[240:241]
	global_store_dwordx4 v[218:219], v[190:193], off nt
	global_store_dwordx4 v[218:219], v[194:197], off offset:64 nt
	global_store_dwordx4 v[218:219], v[234:237], off offset:512 nt
	global_store_dwordx4 v[218:219], v[238:241], off offset:576 nt
	v_cvt_pk_bf16_f32 v20, v190, v191
	v_cvt_pk_bf16_f32 v21, v192, v193
	v_cvt_pk_bf16_f32 v16, v194, v195
	v_cvt_pk_bf16_f32 v17, v196, v197
	v_cvt_pk_bf16_f32 v12, v234, v235
	v_cvt_pk_bf16_f32 v13, v236, v237
	v_cvt_pk_bf16_f32 v8, v238, v239
	v_cvt_pk_bf16_f32 v9, v240, v241
	global_store_dwordx2 v[242:243], v[20:21], off
	global_store_dwordx2 v[242:243], v[16:17], off offset:32
	global_store_dwordx2 v[242:243], v[12:13], off offset:256
	global_store_dwordx2 v[242:243], v[8:9], off offset:288
	s_branch .LBB0_1481
.Lmy_epi_p4_nobf:
	ds_bpermute_b32 v132, v198, v132
	ds_bpermute_b32 v133, v198, v133
	ds_bpermute_b32 v134, v198, v134
	ds_bpermute_b32 v135, v198, v135
	ds_bpermute_b32 v128, v198, v128
	ds_bpermute_b32 v129, v198, v129
	ds_bpermute_b32 v130, v198, v130
	ds_bpermute_b32 v131, v198, v131
	ds_bpermute_b32 v124, v198, v124
	ds_bpermute_b32 v125, v198, v125
	ds_bpermute_b32 v126, v198, v126
	ds_bpermute_b32 v127, v198, v127
	ds_bpermute_b32 v120, v198, v120
	ds_bpermute_b32 v121, v198, v121
	ds_bpermute_b32 v122, v198, v122
	ds_bpermute_b32 v123, v198, v123
	s_waitcnt vmcnt(8)
	s_waitcnt lgkmcnt(0)
	v_pk_fma_f32 v[152:153], v[132:133], v[148:149], v[152:153]
	v_pk_fma_f32 v[154:155], v[134:135], v[150:151], v[154:155]
	v_pk_fma_f32 v[156:157], v[128:129], v[144:145], v[156:157]
	v_pk_fma_f32 v[158:159], v[130:131], v[146:147], v[158:159]
	v_pk_fma_f32 v[160:161], v[124:125], v[140:141], v[160:161]
	v_pk_fma_f32 v[162:163], v[126:127], v[142:143], v[162:163]
	v_pk_fma_f32 v[164:165], v[120:121], v[136:137], v[164:165]
	v_pk_fma_f32 v[166:167], v[122:123], v[138:139], v[166:167]
	global_store_dwordx4 v[218:219], v[152:155], off nt
	global_store_dwordx4 v[218:219], v[156:159], off offset:64 nt
	global_store_dwordx4 v[218:219], v[160:163], off offset:512 nt
	global_store_dwordx4 v[218:219], v[164:167], off offset:576 nt
	s_mov_b32 s30, 0x10000
	s_mov_b32 s31, 0
	v_lshl_add_u64 v[218:219], v[218:219], 0, s[30:31]
	global_load_dwordx4 v[152:155], v[200:201], off nt
	global_load_dwordx4 v[156:159], v[200:201], off offset:64 nt
	global_load_dwordx4 v[160:163], v[200:201], off offset:512 nt
	global_load_dwordx4 v[164:167], v[200:201], off offset:576 nt
	s_mov_b32 s30, 0x50000
	s_mov_b32 s31, 0
	v_lshl_add_u64 v[200:201], v[200:201], 0, s[30:31]
	global_load_dwordx4 v[132:135], v[200:201], off nt
	global_load_dwordx4 v[128:131], v[200:201], off offset:64 nt
	global_load_dwordx4 v[124:127], v[200:201], off offset:512 nt
	global_load_dwordx4 v[120:123], v[200:201], off offset:576 nt
	s_mov_b32 s30, 0x10000
	s_mov_b32 s31, 0
	v_lshl_add_u64 v[200:201], v[200:201], 0, s[30:31]
	ds_bpermute_b32 v116, v198, v116
	ds_bpermute_b32 v117, v198, v117
	ds_bpermute_b32 v118, v198, v118
	ds_bpermute_b32 v119, v198, v119
	ds_bpermute_b32 v112, v198, v112
	ds_bpermute_b32 v113, v198, v113
	ds_bpermute_b32 v114, v198, v114
	ds_bpermute_b32 v115, v198, v115
	ds_bpermute_b32 v108, v198, v108
	ds_bpermute_b32 v109, v198, v109
	ds_bpermute_b32 v110, v198, v110
	ds_bpermute_b32 v111, v198, v111
	ds_bpermute_b32 v104, v198, v104
	ds_bpermute_b32 v105, v198, v105
	ds_bpermute_b32 v106, v198, v106
	ds_bpermute_b32 v107, v198, v107
	s_waitcnt vmcnt(16)
; __device__ __forceinline__ unsigned pk2(float lo, float hi) { const f32v2_t f = {lo, hi}; const bf16v2_t b = __builtin_convertvector(f, bf16v2_t); return __builtin_bit_cast(unsigned, b); }
;     __device__ __forceinline__ void operator()(const f32x4 (&acc)[2][2][4][2], const int upm, const int upn, const int usplit, int wr, int wc, int fr, int fq) const {
;     ...
; #pragma unroll
;         for (int ai = 0; ai < 2; ++ai)
; #pragma unroll
;             for (int mh = 0; mh < 2; ++mh) {
;                 f32x4 xv[2][2][2];
; #pragma unroll
;                 for (int m = 0; m < 2; ++m)
; #pragma unroll
;                     for (int bj = 0; bj < 2; ++bj)
; #pragma unroll
;                         for (int n = 0; n < 2; ++n) xv[m][bj][n] = *(const f32x4*)(sb + (size_t)(row0 + ai * HALF + (mh * 2 + m) * 16) * DM + col0 + bj * HALF + n * 16);
;                 __builtin_amdgcn_sched_barrier(0);
; #pragma unroll
;                 for (int m = 0; m < 2; ++m)
; #pragma unroll
;                     for (int bj = 0; bj < 2; ++bj)
; #pragma unroll
;                         for (int n = 0; n < 2; ++n) {
;                             const size_t o = (size_t)(row0 + ai * HALF + (mh * 2 + m) * 16) * DM + col0 + bj * HALF + n * 16;
;                             const f32x4 r = xv[m][bj][n] + gv[bj][n] * acc[ai][bj][mh * 2 + m][n];
;                             *(f32x4*)(db + o) = r;
;                             if (xb && lat) { u32x2 pk; pk.x = pk2(r[0], r[1]); pk.y = pk2(r[2], r[3]); *(u32x2*)(xb + o) = pk; }
;                         }
	s_waitcnt lgkmcnt(0)
	v_pk_fma_f32 v[168:169], v[116:117], v[148:149], v[168:169]
	v_pk_fma_f32 v[170:171], v[118:119], v[150:151], v[170:171]
	v_pk_fma_f32 v[172:173], v[112:113], v[144:145], v[172:173]
	v_pk_fma_f32 v[174:175], v[114:115], v[146:147], v[174:175]
	v_pk_fma_f32 v[176:177], v[108:109], v[140:141], v[176:177]
	v_pk_fma_f32 v[178:179], v[110:111], v[142:143], v[178:179]
	v_pk_fma_f32 v[180:181], v[104:105], v[136:137], v[180:181]
	v_pk_fma_f32 v[182:183], v[106:107], v[138:139], v[182:183]
	global_store_dwordx4 v[218:219], v[168:171], off nt
	global_store_dwordx4 v[218:219], v[172:175], off offset:64 nt
	global_store_dwordx4 v[218:219], v[176:179], off offset:512 nt
	global_store_dwordx4 v[218:219], v[180:183], off offset:576 nt
	s_mov_b32 s30, 0x10000
	s_mov_b32 s31, 0
	v_lshl_add_u64 v[218:219], v[218:219], 0, s[30:31]
	global_load_dwordx4 v[168:171], v[200:201], off nt
	global_load_dwordx4 v[172:175], v[200:201], off offset:64 nt
	global_load_dwordx4 v[176:179], v[200:201], off offset:512 nt
	global_load_dwordx4 v[180:183], v[200:201], off offset:576 nt
	s_mov_b32 s30, 0x10000
	s_mov_b32 s31, 0
	v_lshl_add_u64 v[200:201], v[200:201], 0, s[30:31]
	global_load_dwordx4 v[116:119], v[200:201], off nt
	global_load_dwordx4 v[112:115], v[200:201], off offset:64 nt
	global_load_dwordx4 v[108:111], v[200:201], off offset:512 nt
	global_load_dwordx4 v[104:107], v[200:201], off offset:576 nt
	s_mov_b32 s30, 0x10000
	s_mov_b32 s31, 0
	v_lshl_add_u64 v[200:201], v[200:201], 0, s[30:31]
	ds_bpermute_b32 v100, v198, v100
	ds_bpermute_b32 v101, v198, v101
	ds_bpermute_b32 v102, v198, v102
	ds_bpermute_b32 v103, v198, v103
	ds_bpermute_b32 v96, v198, v96
	ds_bpermute_b32 v97, v198, v97
	ds_bpermute_b32 v98, v198, v98
	ds_bpermute_b32 v99, v198, v99
	ds_bpermute_b32 v92, v198, v92
	ds_bpermute_b32 v93, v198, v93
	ds_bpermute_b32 v94, v198, v94
	ds_bpermute_b32 v95, v198, v95
	ds_bpermute_b32 v88, v198, v88
	ds_bpermute_b32 v89, v198, v89
	ds_bpermute_b32 v90, v198, v90
	ds_bpermute_b32 v91, v198, v91
	s_waitcnt vmcnt(24)
	s_waitcnt lgkmcnt(0)
	v_pk_fma_f32 v[190:191], v[100:101], v[148:149], v[190:191]
	v_pk_fma_f32 v[192:193], v[102:103], v[150:151], v[192:193]
	v_pk_fma_f32 v[194:195], v[96:97], v[144:145], v[194:195]
	v_pk_fma_f32 v[196:197], v[98:99], v[146:147], v[196:197]
	v_pk_fma_f32 v[234:235], v[92:93], v[140:141], v[234:235]
	v_pk_fma_f32 v[236:237], v[94:95], v[142:143], v[236:237]
	v_pk_fma_f32 v[238:239], v[88:89], v[136:137], v[238:239]
	v_pk_fma_f32 v[240:241], v[90:91], v[138:139], v[240:241]
	global_store_dwordx4 v[218:219], v[190:193], off nt
	global_store_dwordx4 v[218:219], v[194:197], off offset:64 nt
	global_store_dwordx4 v[218:219], v[234:237], off offset:512 nt
	global_store_dwordx4 v[218:219], v[238:241], off offset:576 nt
	s_mov_b32 s30, 0x10000
	s_mov_b32 s31, 0
	v_lshl_add_u64 v[218:219], v[218:219], 0, s[30:31]
	global_load_dwordx4 v[190:193], v[200:201], off nt
	global_load_dwordx4 v[194:197], v[200:201], off offset:64 nt
	global_load_dwordx4 v[234:237], v[200:201], off offset:512 nt
	global_load_dwordx4 v[238:241], v[200:201], off offset:576 nt
	ds_bpermute_b32 v84, v198, v84
	ds_bpermute_b32 v85, v198, v85
	ds_bpermute_b32 v86, v198, v86
	ds_bpermute_b32 v87, v198, v87
	ds_bpermute_b32 v80, v198, v80
	ds_bpermute_b32 v81, v198, v81
	ds_bpermute_b32 v82, v198, v82
	ds_bpermute_b32 v83, v198, v83
	ds_bpermute_b32 v76, v198, v76
	ds_bpermute_b32 v77, v198, v77
	ds_bpermute_b32 v78, v198, v78
	ds_bpermute_b32 v79, v198, v79
	ds_bpermute_b32 v72, v198, v72
	ds_bpermute_b32 v73, v198, v73
	ds_bpermute_b32 v74, v198, v74
	ds_bpermute_b32 v75, v198, v75
	s_waitcnt vmcnt(24)
	s_waitcnt lgkmcnt(0)
	v_pk_fma_f32 v[152:153], v[84:85], v[148:149], v[152:153]
	v_pk_fma_f32 v[154:155], v[86:87], v[150:151], v[154:155]
	v_pk_fma_f32 v[156:157], v[80:81], v[144:145], v[156:157]
	v_pk_fma_f32 v[158:159], v[82:83], v[146:147], v[158:159]
	v_pk_fma_f32 v[160:161], v[76:77], v[140:141], v[160:161]
	v_pk_fma_f32 v[162:163], v[78:79], v[142:143], v[162:163]
	v_pk_fma_f32 v[164:165], v[72:73], v[136:137], v[164:165]
	v_pk_fma_f32 v[166:167], v[74:75], v[138:139], v[166:167]
	global_store_dwordx4 v[218:219], v[152:155], off nt
	global_store_dwordx4 v[218:219], v[156:159], off offset:64 nt
	global_store_dwordx4 v[218:219], v[160:163], off offset:512 nt
	global_store_dwordx4 v[218:219], v[164:167], off offset:576 nt
	s_mov_b32 s30, 0x50000
	s_mov_b32 s31, 0
	v_lshl_add_u64 v[218:219], v[218:219], 0, s[30:31]
	ds_bpermute_b32 v68, v198, v68
	ds_bpermute_b32 v69, v198, v69
	ds_bpermute_b32 v70, v198, v70
	ds_bpermute_b32 v71, v198, v71
	ds_bpermute_b32 v64, v198, v64
	ds_bpermute_b32 v65, v198, v65
	ds_bpermute_b32 v66, v198, v66
	ds_bpermute_b32 v67, v198, v67
	ds_bpermute_b32 v60, v198, v60
	ds_bpermute_b32 v61, v198, v61
	ds_bpermute_b32 v62, v198, v62
	ds_bpermute_b32 v63, v198, v63
	ds_bpermute_b32 v56, v198, v56
	ds_bpermute_b32 v57, v198, v57
	ds_bpermute_b32 v58, v198, v58
	ds_bpermute_b32 v59, v198, v59
	s_waitcnt vmcnt(24)
; __device__ __forceinline__ unsigned pk2(float lo, float hi) { const f32v2_t f = {lo, hi}; const bf16v2_t b = __builtin_convertvector(f, bf16v2_t); return __builtin_bit_cast(unsigned, b); }
;     __device__ __forceinline__ void operator()(const f32x4 (&acc)[2][2][4][2], const int upm, const int upn, const int usplit, int wr, int wc, int fr, int fq) const {
;     ...
; #pragma unroll
;         for (int ai = 0; ai < 2; ++ai)
; #pragma unroll
;             for (int mh = 0; mh < 2; ++mh) {
;                 f32x4 xv[2][2][2];
; #pragma unroll
;                 for (int m = 0; m < 2; ++m)
; #pragma unroll
;                     for (int bj = 0; bj < 2; ++bj)
; #pragma unroll
;                         for (int n = 0; n < 2; ++n) xv[m][bj][n] = *(const f32x4*)(sb + (size_t)(row0 + ai * HALF + (mh * 2 + m) * 16) * DM + col0 + bj * HALF + n * 16);
;                 __builtin_amdgcn_sched_barrier(0);
; #pragma unroll
;                 for (int m = 0; m < 2; ++m)
; #pragma unroll
;                     for (int bj = 0; bj < 2; ++bj)
; #pragma unroll
;                         for (int n = 0; n < 2; ++n) {
;                             const size_t o = (size_t)(row0 + ai * HALF + (mh * 2 + m) * 16) * DM + col0 + bj * HALF + n * 16;
;                             const f32x4 r = xv[m][bj][n] + gv[bj][n] * acc[ai][bj][mh * 2 + m][n];
;                             *(f32x4*)(db + o) = r;
;                             if (xb && lat) { u32x2 pk; pk.x = pk2(r[0], r[1]); pk.y = pk2(r[2], r[3]); *(u32x2*)(xb + o) = pk; }
;                         }
	s_waitcnt lgkmcnt(0)
	v_pk_fma_f32 v[132:133], v[68:69], v[148:149], v[132:133]
	v_pk_fma_f32 v[134:135], v[70:71], v[150:151], v[134:135]
	v_pk_fma_f32 v[128:129], v[64:65], v[144:145], v[128:129]
	v_pk_fma_f32 v[130:131], v[66:67], v[146:147], v[130:131]
	v_pk_fma_f32 v[124:125], v[60:61], v[140:141], v[124:125]
	v_pk_fma_f32 v[126:127], v[62:63], v[142:143], v[126:127]
	v_pk_fma_f32 v[120:121], v[56:57], v[136:137], v[120:121]
	v_pk_fma_f32 v[122:123], v[58:59], v[138:139], v[122:123]
	global_store_dwordx4 v[218:219], v[132:135], off nt
	global_store_dwordx4 v[218:219], v[128:131], off offset:64 nt
	global_store_dwordx4 v[218:219], v[124:127], off offset:512 nt
	global_store_dwordx4 v[218:219], v[120:123], off offset:576 nt
	s_mov_b32 s30, 0x10000
	s_mov_b32 s31, 0
	v_lshl_add_u64 v[218:219], v[218:219], 0, s[30:31]
	ds_bpermute_b32 v52, v198, v52
	ds_bpermute_b32 v53, v198, v53
	ds_bpermute_b32 v54, v198, v54
	ds_bpermute_b32 v55, v198, v55
	ds_bpermute_b32 v48, v198, v48
	ds_bpermute_b32 v49, v198, v49
	ds_bpermute_b32 v50, v198, v50
	ds_bpermute_b32 v51, v198, v51
	ds_bpermute_b32 v44, v198, v44
	ds_bpermute_b32 v45, v198, v45
	ds_bpermute_b32 v46, v198, v46
	ds_bpermute_b32 v47, v198, v47
	ds_bpermute_b32 v40, v198, v40
	ds_bpermute_b32 v41, v198, v41
	ds_bpermute_b32 v42, v198, v42
	ds_bpermute_b32 v43, v198, v43
	s_waitcnt vmcnt(20)
	s_waitcnt lgkmcnt(0)
	v_pk_fma_f32 v[168:169], v[52:53], v[148:149], v[168:169]
	v_pk_fma_f32 v[170:171], v[54:55], v[150:151], v[170:171]
	v_pk_fma_f32 v[172:173], v[48:49], v[144:145], v[172:173]
	v_pk_fma_f32 v[174:175], v[50:51], v[146:147], v[174:175]
	v_pk_fma_f32 v[176:177], v[44:45], v[140:141], v[176:177]
	v_pk_fma_f32 v[178:179], v[46:47], v[142:143], v[178:179]
	v_pk_fma_f32 v[180:181], v[40:41], v[136:137], v[180:181]
	v_pk_fma_f32 v[182:183], v[42:43], v[138:139], v[182:183]
	global_store_dwordx4 v[218:219], v[168:171], off nt
	global_store_dwordx4 v[218:219], v[172:175], off offset:64 nt
	global_store_dwordx4 v[218:219], v[176:179], off offset:512 nt
	global_store_dwordx4 v[218:219], v[180:183], off offset:576 nt
	s_mov_b32 s30, 0x10000
	s_mov_b32 s31, 0
	v_lshl_add_u64 v[218:219], v[218:219], 0, s[30:31]
	ds_bpermute_b32 v36, v198, v36
	ds_bpermute_b32 v37, v198, v37
	ds_bpermute_b32 v38, v198, v38
	ds_bpermute_b32 v39, v198, v39
	ds_bpermute_b32 v32, v198, v32
	ds_bpermute_b32 v33, v198, v33
	ds_bpermute_b32 v34, v198, v34
	ds_bpermute_b32 v35, v198, v35
	ds_bpermute_b32 v28, v198, v28
	ds_bpermute_b32 v29, v198, v29
	ds_bpermute_b32 v30, v198, v30
	ds_bpermute_b32 v31, v198, v31
	ds_bpermute_b32 v24, v198, v24
	ds_bpermute_b32 v25, v198, v25
	ds_bpermute_b32 v26, v198, v26
	ds_bpermute_b32 v27, v198, v27
	s_waitcnt vmcnt(20)
	s_waitcnt lgkmcnt(0)
	v_pk_fma_f32 v[116:117], v[36:37], v[148:149], v[116:117]
	v_pk_fma_f32 v[118:119], v[38:39], v[150:151], v[118:119]
	v_pk_fma_f32 v[112:113], v[32:33], v[144:145], v[112:113]
	v_pk_fma_f32 v[114:115], v[34:35], v[146:147], v[114:115]
	v_pk_fma_f32 v[108:109], v[28:29], v[140:141], v[108:109]
	v_pk_fma_f32 v[110:111], v[30:31], v[142:143], v[110:111]
	v_pk_fma_f32 v[104:105], v[24:25], v[136:137], v[104:105]
	v_pk_fma_f32 v[106:107], v[26:27], v[138:139], v[106:107]
	global_store_dwordx4 v[218:219], v[116:119], off nt
	global_store_dwordx4 v[218:219], v[112:115], off offset:64 nt
	global_store_dwordx4 v[218:219], v[108:111], off offset:512 nt
	global_store_dwordx4 v[218:219], v[104:107], off offset:576 nt
	s_mov_b32 s30, 0x10000
	s_mov_b32 s31, 0
	v_lshl_add_u64 v[218:219], v[218:219], 0, s[30:31]
	ds_bpermute_b32 v20, v198, v20
	ds_bpermute_b32 v21, v198, v21
	ds_bpermute_b32 v22, v198, v22
	ds_bpermute_b32 v23, v198, v23
	ds_bpermute_b32 v16, v198, v16
	ds_bpermute_b32 v17, v198, v17
	ds_bpermute_b32 v18, v198, v18
	ds_bpermute_b32 v19, v198, v19
	ds_bpermute_b32 v12, v198, v12
	ds_bpermute_b32 v13, v198, v13
	ds_bpermute_b32 v14, v198, v14
	ds_bpermute_b32 v15, v198, v15
	ds_bpermute_b32 v8, v198, v8
	ds_bpermute_b32 v9, v198, v9
	ds_bpermute_b32 v10, v198, v10
	ds_bpermute_b32 v11, v198, v11
	s_waitcnt vmcnt(16)
	s_waitcnt lgkmcnt(0)
	v_pk_fma_f32 v[190:191], v[20:21], v[148:149], v[190:191]
	v_pk_fma_f32 v[192:193], v[22:23], v[150:151], v[192:193]
	v_pk_fma_f32 v[194:195], v[16:17], v[144:145], v[194:195]
	v_pk_fma_f32 v[196:197], v[18:19], v[146:147], v[196:197]
	v_pk_fma_f32 v[234:235], v[12:13], v[140:141], v[234:235]
	v_pk_fma_f32 v[236:237], v[14:15], v[142:143], v[236:237]
	v_pk_fma_f32 v[238:239], v[8:9], v[136:137], v[238:239]
	v_pk_fma_f32 v[240:241], v[10:11], v[138:139], v[240:241]
	global_store_dwordx4 v[218:219], v[190:193], off nt
	global_store_dwordx4 v[218:219], v[194:197], off offset:64 nt
	global_store_dwordx4 v[218:219], v[234:237], off offset:512 nt
	global_store_dwordx4 v[218:219], v[238:241], off offset:576 nt
	s_branch .LBB0_1481

;     __device__ __forceinline__ void operator()(const f32x4 (&acc)[2][2][4][2], const int upm, const int upn, const int usplit, int wr, int wc, int fr, int fq) const {
;         const int row0 = upm * BM + wr * 64 + fr, col0 = upn * BM + wc * 32 + 4 * fq;
;         if (usplit) {
;             float* sl = slab + ((size_t)(usplit - 1) * NCTX + (row0 - NLAT)) * DM + col0;
; #pragma unroll
;             for (int ai = 0; ai < 2; ++ai)
; #pragma unroll
;                 for (int m = 0; m < 4; ++m)
; #pragma unroll
;                     for (int bj = 0; bj < 2; ++bj)
; #pragma unroll
;                         for (int n = 0; n < 2; ++n) *(f32x4*)(sl + (size_t)(ai * HALF + m * 16) * DM + bj * HALF + n * 16) = acc[ai][bj][m][n];
;             return;
;         }
;         const bool lat = upm * BM < NLAT; const int b = lat ? ((upm * BM) >> 11) : 16;
;         const float* gp = gate + (size_t)b * 6144 + col0;
;         f32x4 gv[2][2];
; #pragma unroll
;         for (int bj = 0; bj < 2; ++bj)
; #pragma unroll
;             for (int n = 0; n < 2; ++n) gv[bj][n] = *(const f32x4*)(gp + bj * HALF + n * 16);
;         const float* sb = lat ? src_lat : src_ctx - (size_t)NLAT * DM; float* db = lat ? dst_lat : dst_ctx - (size_t)NLAT * DM;
; #pragma unroll
;         for (int ai = 0; ai < 2; ++ai)
; #pragma unroll
;             for (int mh = 0; mh < 2; ++mh) {
;                 f32x4 xv[2][2][2];
; #pragma unroll
;                 for (int m = 0; m < 2; ++m)
; #pragma unroll
;                     for (int bj = 0; bj < 2; ++bj)
; #pragma unroll
;                         for (int n = 0; n < 2; ++n) xv[m][bj][n] = *(const f32x4*)(sb + (size_t)(row0 + ai * HALF + (mh * 2 + m) * 16) * DM + col0 + bj * HALF + n * 16);
;                 __builtin_amdgcn_sched_barrier(0);
; #pragma unroll
;                 for (int m = 0; m < 2; ++m)
; #pragma unroll
;                     for (int bj = 0; bj < 2; ++bj)
; #pragma unroll
;                         for (int n = 0; n < 2; ++n) {
;                             const size_t o = (size_t)(row0 + ai * HALF + (mh * 2 + m) * 16) * DM + col0 + bj * HALF + n * 16;
;                             const f32x4 r = xv[m][bj][n] + gv[bj][n] * acc[ai][bj][mh * 2 + m][n];
;                             *(f32x4*)(db + o) = r;
;                             if (xb && lat) { u32x2 pk; pk.x = pk2(r[0], r[1]); pk.y = pk2(r[2], r[3]); *(u32x2*)(xb + o) = pk; }
.LBB0_1866:
	s_lshl_b64 s[0:1], s[60:61], 2
	s_add_u32 s0, s21, s0
	s_addc_u32 s1, s69, s1
	v_mbcnt_lo_u32_b32 v152, -1, 0
	v_mbcnt_hi_u32_b32 v152, -1, v152
	v_and_b32_e32 v153, 15, v152
	v_lshrrev_b32_e32 v154, 2, v152
	v_lshrrev_b32_e32 v155, 4, v152
	v_and_b32_e32 v156, 3, v152
	v_sub_u32_e32 v192, v192, v153
	v_add_u32_e32 v192, v192, v154
	v_ashrrev_i32_e32 v193, 31, v192
	v_sub_u32_e32 v157, v156, v155
	v_lshl_add_u32 v190, v157, 2, v190
	v_ashrrev_i32_e32 v191, 31, v190
	v_lshl_add_u32 v158, v156, 4, v154
	v_lshlrev_b64 v[198:199], 2, v[190:191]
	v_lshl_add_u64 v[242:243], s[0:1], 0, v[198:199]
	v_lshl_add_u64 v[200:201], s[58:59], 0, v[198:199]
	v_lshl_add_u64 v[218:219], s[58:59], 0, v[198:199]
	v_lshlrev_b64 v[198:199], 12, v[192:193]
	v_lshl_add_u64 v[200:201], v[200:201], 0, v[198:199]
	v_lshl_add_u64 v[218:219], v[218:219], 0, v[198:199]
	global_load_dwordx4 v[148:151], v[242:243], off
	global_load_dwordx4 v[144:147], v[242:243], off offset:64
	global_load_dwordx4 v[140:143], v[242:243], off offset:512
	global_load_dwordx4 v[136:139], v[242:243], off offset:576
	v_lshlrev_b64 v[198:199], 1, v[190:191]
	v_lshl_add_u64 v[242:243], s[40:41], 0, v[198:199]
	v_lshlrev_b64 v[198:199], 11, v[192:193]
	v_lshl_add_u64 v[242:243], v[242:243], 0, v[198:199]
	v_lshlrev_b32_e32 v198, 2, v158
	global_load_dwordx4 v[152:155], v[200:201], off nt
	global_load_dwordx4 v[156:159], v[200:201], off offset:64 nt
	global_load_dwordx4 v[160:163], v[200:201], off offset:512 nt
	global_load_dwordx4 v[164:167], v[200:201], off offset:576 nt
	s_mov_b32 s0, 0x10000
	s_mov_b32 s1, 0
	v_lshl_add_u64 v[200:201], v[200:201], 0, s[0:1]
	global_load_dwordx4 v[168:171], v[200:201], off nt
	global_load_dwordx4 v[172:175], v[200:201], off offset:64 nt
	global_load_dwordx4 v[176:179], v[200:201], off offset:512 nt
	global_load_dwordx4 v[180:183], v[200:201], off offset:576 nt
	s_mov_b32 s0, 0x10000
	s_mov_b32 s1, 0
	v_lshl_add_u64 v[200:201], v[200:201], 0, s[0:1]
	global_load_dwordx4 v[190:193], v[200:201], off nt
	global_load_dwordx4 v[194:197], v[200:201], off offset:64 nt
	global_load_dwordx4 v[234:237], v[200:201], off offset:512 nt
	global_load_dwordx4 v[238:241], v[200:201], off offset:576 nt
	s_mov_b32 s0, 0x10000
	s_mov_b32 s1, 0
	v_lshl_add_u64 v[200:201], v[200:201], 0, s[0:1]
	s_and_b64 s[0:1], s[46:47], s[56:57]
	s_xor_b64 s[56:57], s[0:1], -1
	s_and_b64 vcc, exec, s[56:57]
	s_cbranch_vccnz .Lmy_epi_p7_nobf
	ds_bpermute_b32 v132, v198, v132
	ds_bpermute_b32 v133, v198, v133
	ds_bpermute_b32 v134, v198, v134
	ds_bpermute_b32 v135, v198, v135
	ds_bpermute_b32 v128, v198, v128
	ds_bpermute_b32 v129, v198, v129
	ds_bpermute_b32 v130, v198, v130
	ds_bpermute_b32 v131, v198, v131
	ds_bpermute_b32 v124, v198, v124
	ds_bpermute_b32 v125, v198, v125
	ds_bpermute_b32 v126, v198, v126
	ds_bpermute_b32 v127, v198, v127
	ds_bpermute_b32 v120, v198, v120
	ds_bpermute_b32 v121, v198, v121
	ds_bpermute_b32 v122, v198, v122
	ds_bpermute_b32 v123, v198, v123
	s_waitcnt vmcnt(8)
	s_waitcnt lgkmcnt(0)
	v_pk_fma_f32 v[152:153], v[132:133], v[148:149], v[152:153]
	v_pk_fma_f32 v[154:155], v[134:135], v[150:151], v[154:155]
	v_pk_fma_f32 v[156:157], v[128:129], v[144:145], v[156:157]
	v_pk_fma_f32 v[158:159], v[130:131], v[146:147], v[158:159]
	v_pk_fma_f32 v[160:161], v[124:125], v[140:141], v[160:161]
	v_pk_fma_f32 v[162:163], v[126:127], v[142:143], v[162:163]
	v_pk_fma_f32 v[164:165], v[120:121], v[136:137], v[164:165]
	v_pk_fma_f32 v[166:167], v[122:123], v[138:139], v[166:167]
	global_store_dwordx4 v[218:219], v[152:155], off nt
	global_store_dwordx4 v[218:219], v[156:159], off offset:64 nt
	global_store_dwordx4 v[218:219], v[160:163], off offset:512 nt
	global_store_dwordx4 v[218:219], v[164:167], off offset:576 nt
	v_cvt_pk_bf16_f32 v132, v152, v153
	v_cvt_pk_bf16_f32 v133, v154, v155
	v_cvt_pk_bf16_f32 v128, v156, v157
	v_cvt_pk_bf16_f32 v129, v158, v159
	v_cvt_pk_bf16_f32 v124, v160, v161
	v_cvt_pk_bf16_f32 v125, v162, v163
	v_cvt_pk_bf16_f32 v120, v164, v165
	v_cvt_pk_bf16_f32 v121, v166, v167
	global_store_dwordx2 v[242:243], v[132:133], off
	global_store_dwordx2 v[242:243], v[128:129], off offset:32
	global_store_dwordx2 v[242:243], v[124:125], off offset:256
	global_store_dwordx2 v[242:243], v[120:121], off offset:288
	s_mov_b32 s0, 0x10000
	s_mov_b32 s1, 0
	v_lshl_add_u64 v[218:219], v[218:219], 0, s[0:1]
	s_mov_b32 s0, 0x8000
	s_mov_b32 s1, 0
	v_lshl_add_u64 v[242:243], v[242:243], 0, s[0:1]
	global_load_dwordx4 v[152:155], v[200:201], off nt
	global_load_dwordx4 v[156:159], v[200:201], off offset:64 nt
	global_load_dwordx4 v[160:163], v[200:201], off offset:512 nt
	global_load_dwordx4 v[164:167], v[200:201], off offset:576 nt
	s_mov_b32 s0, 0x50000
	s_mov_b32 s1, 0
	v_lshl_add_u64 v[200:201], v[200:201], 0, s[0:1]
	global_load_dwordx4 v[132:135], v[200:201], off nt
	global_load_dwordx4 v[128:131], v[200:201], off offset:64 nt
	global_load_dwordx4 v[124:127], v[200:201], off offset:512 nt
	global_load_dwordx4 v[120:123], v[200:201], off offset:576 nt
	s_mov_b32 s0, 0x10000
	s_mov_b32 s1, 0
	v_lshl_add_u64 v[200:201], v[200:201], 0, s[0:1]
	ds_bpermute_b32 v116, v198, v116
	ds_bpermute_b32 v117, v198, v117
	ds_bpermute_b32 v118, v198, v118
	ds_bpermute_b32 v119, v198, v119
	ds_bpermute_b32 v112, v198, v112
	ds_bpermute_b32 v113, v198, v113
	ds_bpermute_b32 v114, v198, v114
	ds_bpermute_b32 v115, v198, v115
	ds_bpermute_b32 v108, v198, v108
	ds_bpermute_b32 v109, v198, v109
	ds_bpermute_b32 v110, v198, v110
	ds_bpermute_b32 v111, v198, v111
	ds_bpermute_b32 v104, v198, v104
	ds_bpermute_b32 v105, v198, v105
	ds_bpermute_b32 v106, v198, v106
	ds_bpermute_b32 v107, v198, v107
	s_waitcnt vmcnt(20)
; __device__ __forceinline__ unsigned pk2(float lo, float hi) { const f32v2_t f = {lo, hi}; const bf16v2_t b = __builtin_convertvector(f, bf16v2_t); return __builtin_bit_cast(unsigned, b); }
;     __device__ __forceinline__ void operator()(const f32x4 (&acc)[2][2][4][2], const int upm, const int upn, const int usplit, int wr, int wc, int fr, int fq) const {
;     ...
; #pragma unroll
;         for (int ai = 0; ai < 2; ++ai)
; #pragma unroll
;             for (int mh = 0; mh < 2; ++mh) {
;                 f32x4 xv[2][2][2];
; #pragma unroll
;                 for (int m = 0; m < 2; ++m)
; #pragma unroll
;                     for (int bj = 0; bj < 2; ++bj)
; #pragma unroll
;                         for (int n = 0; n < 2; ++n) xv[m][bj][n] = *(const f32x4*)(sb + (size_t)(row0 + ai * HALF + (mh * 2 + m) * 16) * DM + col0 + bj * HALF + n * 16);
;                 __builtin_amdgcn_sched_barrier(0);
; #pragma unroll
;                 for (int m = 0; m < 2; ++m)
; #pragma unroll
;                     for (int bj = 0; bj < 2; ++bj)
; #pragma unroll
;                         for (int n = 0; n < 2; ++n) {
;                             const size_t o = (size_t)(row0 + ai * HALF + (mh * 2 + m) * 16) * DM + col0 + bj * HALF + n * 16;
;                             const f32x4 r = xv[m][bj][n] + gv[bj][n] * acc[ai][bj][mh * 2 + m][n];
;                             *(f32x4*)(db + o) = r;
;                             if (xb && lat) { u32x2 pk; pk.x = pk2(r[0], r[1]); pk.y = pk2(r[2], r[3]); *(u32x2*)(xb + o) = pk; }
;                         }
	s_waitcnt lgkmcnt(0)
	v_pk_fma_f32 v[168:169], v[116:117], v[148:149], v[168:169]
	v_pk_fma_f32 v[170:171], v[118:119], v[150:151], v[170:171]
	v_pk_fma_f32 v[172:173], v[112:113], v[144:145], v[172:173]
	v_pk_fma_f32 v[174:175], v[114:115], v[146:147], v[174:175]
	v_pk_fma_f32 v[176:177], v[108:109], v[140:141], v[176:177]
	v_pk_fma_f32 v[178:179], v[110:111], v[142:143], v[178:179]
	v_pk_fma_f32 v[180:181], v[104:105], v[136:137], v[180:181]
	v_pk_fma_f32 v[182:183], v[106:107], v[138:139], v[182:183]
	global_store_dwordx4 v[218:219], v[168:171], off nt
	global_store_dwordx4 v[218:219], v[172:175], off offset:64 nt
	global_store_dwordx4 v[218:219], v[176:179], off offset:512 nt
	global_store_dwordx4 v[218:219], v[180:183], off offset:576 nt
	v_cvt_pk_bf16_f32 v116, v168, v169
	v_cvt_pk_bf16_f32 v117, v170, v171
	v_cvt_pk_bf16_f32 v112, v172, v173
	v_cvt_pk_bf16_f32 v113, v174, v175
	v_cvt_pk_bf16_f32 v108, v176, v177
	v_cvt_pk_bf16_f32 v109, v178, v179
	v_cvt_pk_bf16_f32 v104, v180, v181
	v_cvt_pk_bf16_f32 v105, v182, v183
	global_store_dwordx2 v[242:243], v[116:117], off
	global_store_dwordx2 v[242:243], v[112:113], off offset:32
	global_store_dwordx2 v[242:243], v[108:109], off offset:256
	global_store_dwordx2 v[242:243], v[104:105], off offset:288
	s_mov_b32 s0, 0x10000
	s_mov_b32 s1, 0
	v_lshl_add_u64 v[218:219], v[218:219], 0, s[0:1]
	s_mov_b32 s0, 0x8000
	s_mov_b32 s1, 0
	v_lshl_add_u64 v[242:243], v[242:243], 0, s[0:1]
	global_load_dwordx4 v[168:171], v[200:201], off nt
	global_load_dwordx4 v[172:175], v[200:201], off offset:64 nt
	global_load_dwordx4 v[176:179], v[200:201], off offset:512 nt
	global_load_dwordx4 v[180:183], v[200:201], off offset:576 nt
	s_mov_b32 s0, 0x10000
	s_mov_b32 s1, 0
	v_lshl_add_u64 v[200:201], v[200:201], 0, s[0:1]
	global_load_dwordx4 v[116:119], v[200:201], off nt
	global_load_dwordx4 v[112:115], v[200:201], off offset:64 nt
	global_load_dwordx4 v[108:111], v[200:201], off offset:512 nt
	global_load_dwordx4 v[104:107], v[200:201], off offset:576 nt
	s_mov_b32 s0, 0x10000
	s_mov_b32 s1, 0
	v_lshl_add_u64 v[200:201], v[200:201], 0, s[0:1]
	ds_bpermute_b32 v100, v198, v100
	ds_bpermute_b32 v101, v198, v101
	ds_bpermute_b32 v102, v198, v102
	ds_bpermute_b32 v103, v198, v103
	ds_bpermute_b32 v96, v198, v96
	ds_bpermute_b32 v97, v198, v97
	ds_bpermute_b32 v98, v198, v98
	ds_bpermute_b32 v99, v198, v99
	ds_bpermute_b32 v92, v198, v92
	ds_bpermute_b32 v93, v198, v93
	ds_bpermute_b32 v94, v198, v94
	ds_bpermute_b32 v95, v198, v95
	ds_bpermute_b32 v88, v198, v88
	ds_bpermute_b32 v89, v198, v89
	ds_bpermute_b32 v90, v198, v90
	ds_bpermute_b32 v91, v198, v91
	s_waitcnt vmcnt(32)
	s_waitcnt lgkmcnt(0)
	v_pk_fma_f32 v[190:191], v[100:101], v[148:149], v[190:191]
	v_pk_fma_f32 v[192:193], v[102:103], v[150:151], v[192:193]
	v_pk_fma_f32 v[194:195], v[96:97], v[144:145], v[194:195]
	v_pk_fma_f32 v[196:197], v[98:99], v[146:147], v[196:197]
	v_pk_fma_f32 v[234:235], v[92:93], v[140:141], v[234:235]
	v_pk_fma_f32 v[236:237], v[94:95], v[142:143], v[236:237]
	v_pk_fma_f32 v[238:239], v[88:89], v[136:137], v[238:239]
	v_pk_fma_f32 v[240:241], v[90:91], v[138:139], v[240:241]
	global_store_dwordx4 v[218:219], v[190:193], off nt
	global_store_dwordx4 v[218:219], v[194:197], off offset:64 nt
	global_store_dwordx4 v[218:219], v[234:237], off offset:512 nt
	global_store_dwordx4 v[218:219], v[238:241], off offset:576 nt
	v_cvt_pk_bf16_f32 v100, v190, v191
	v_cvt_pk_bf16_f32 v101, v192, v193
	v_cvt_pk_bf16_f32 v96, v194, v195
	v_cvt_pk_bf16_f32 v97, v196, v197
	v_cvt_pk_bf16_f32 v92, v234, v235
	v_cvt_pk_bf16_f32 v93, v236, v237
	v_cvt_pk_bf16_f32 v88, v238, v239
	v_cvt_pk_bf16_f32 v89, v240, v241
	global_store_dwordx2 v[242:243], v[100:101], off
	global_store_dwordx2 v[242:243], v[96:97], off offset:32
	global_store_dwordx2 v[242:243], v[92:93], off offset:256
	global_store_dwordx2 v[242:243], v[88:89], off offset:288
	s_mov_b32 s0, 0x10000
	s_mov_b32 s1, 0
	v_lshl_add_u64 v[218:219], v[218:219], 0, s[0:1]
	s_mov_b32 s0, 0x8000
	s_mov_b32 s1, 0
	v_lshl_add_u64 v[242:243], v[242:243], 0, s[0:1]
	global_load_dwordx4 v[190:193], v[200:201], off nt
	global_load_dwordx4 v[194:197], v[200:201], off offset:64 nt
	global_load_dwordx4 v[234:237], v[200:201], off offset:512 nt
	global_load_dwordx4 v[238:241], v[200:201], off offset:576 nt
	ds_bpermute_b32 v84, v198, v84
	ds_bpermute_b32 v85, v198, v85
	ds_bpermute_b32 v86, v198, v86
	ds_bpermute_b32 v87, v198, v87
	ds_bpermute_b32 v80, v198, v80
	ds_bpermute_b32 v81, v198, v81
	ds_bpermute_b32 v82, v198, v82
	ds_bpermute_b32 v83, v198, v83
	ds_bpermute_b32 v76, v198, v76
	ds_bpermute_b32 v77, v198, v77
	ds_bpermute_b32 v78, v198, v78
	ds_bpermute_b32 v79, v198, v79
	ds_bpermute_b32 v72, v198, v72
	ds_bpermute_b32 v73, v198, v73
	ds_bpermute_b32 v74, v198, v74
	ds_bpermute_b32 v75, v198, v75
	s_waitcnt vmcnt(32)
	s_waitcnt lgkmcnt(0)
; __device__ __forceinline__ unsigned pk2(float lo, float hi) { const f32v2_t f = {lo, hi}; const bf16v2_t b = __builtin_convertvector(f, bf16v2_t); return __builtin_bit_cast(unsigned, b); }
;     __device__ __forceinline__ void operator()(const f32x4 (&acc)[2][2][4][2], const int upm, const int upn, const int usplit, int wr, int wc, int fr, int fq) const {
;     ...
; #pragma unroll
;         for (int ai = 0; ai < 2; ++ai)
; #pragma unroll
;             for (int mh = 0; mh < 2; ++mh) {
;                 f32x4 xv[2][2][2];
; #pragma unroll
;                 for (int m = 0; m < 2; ++m)
; #pragma unroll
;                     for (int bj = 0; bj < 2; ++bj)
; #pragma unroll
;                         for (int n = 0; n < 2; ++n) xv[m][bj][n] = *(const f32x4*)(sb + (size_t)(row0 + ai * HALF + (mh * 2 + m) * 16) * DM + col0 + bj * HALF + n * 16);
;                 __builtin_amdgcn_sched_barrier(0);
; #pragma unroll
;                 for (int m = 0; m < 2; ++m)
; #pragma unroll
;                     for (int bj = 0; bj < 2; ++bj)
; #pragma unroll
;                         for (int n = 0; n < 2; ++n) {
;                             const size_t o = (size_t)(row0 + ai * HALF + (mh * 2 + m) * 16) * DM + col0 + bj * HALF + n * 16;
;                             const f32x4 r = xv[m][bj][n] + gv[bj][n] * acc[ai][bj][mh * 2 + m][n];
;                             *(f32x4*)(db + o) = r;
;                             if (xb && lat) { u32x2 pk; pk.x = pk2(r[0], r[1]); pk.y = pk2(r[2], r[3]); *(u32x2*)(xb + o) = pk; }
;                         }
	v_pk_fma_f32 v[152:153], v[84:85], v[148:149], v[152:153]
	v_pk_fma_f32 v[154:155], v[86:87], v[150:151], v[154:155]
	v_pk_fma_f32 v[156:157], v[80:81], v[144:145], v[156:157]
	v_pk_fma_f32 v[158:159], v[82:83], v[146:147], v[158:159]
	v_pk_fma_f32 v[160:161], v[76:77], v[140:141], v[160:161]
	v_pk_fma_f32 v[162:163], v[78:79], v[142:143], v[162:163]
	v_pk_fma_f32 v[164:165], v[72:73], v[136:137], v[164:165]
	v_pk_fma_f32 v[166:167], v[74:75], v[138:139], v[166:167]
	global_store_dwordx4 v[218:219], v[152:155], off nt
	global_store_dwordx4 v[218:219], v[156:159], off offset:64 nt
	global_store_dwordx4 v[218:219], v[160:163], off offset:512 nt
	global_store_dwordx4 v[218:219], v[164:167], off offset:576 nt
	v_cvt_pk_bf16_f32 v84, v152, v153
	v_cvt_pk_bf16_f32 v85, v154, v155
	v_cvt_pk_bf16_f32 v80, v156, v157
	v_cvt_pk_bf16_f32 v81, v158, v159
	v_cvt_pk_bf16_f32 v76, v160, v161
	v_cvt_pk_bf16_f32 v77, v162, v163
	v_cvt_pk_bf16_f32 v72, v164, v165
	v_cvt_pk_bf16_f32 v73, v166, v167
	global_store_dwordx2 v[242:243], v[84:85], off
	global_store_dwordx2 v[242:243], v[80:81], off offset:32
	global_store_dwordx2 v[242:243], v[76:77], off offset:256
	global_store_dwordx2 v[242:243], v[72:73], off offset:288
	s_mov_b32 s0, 0x50000
	s_mov_b32 s1, 0
	v_lshl_add_u64 v[218:219], v[218:219], 0, s[0:1]
	s_mov_b32 s0, 0x28000
	s_mov_b32 s1, 0
	v_lshl_add_u64 v[242:243], v[242:243], 0, s[0:1]
	ds_bpermute_b32 v68, v198, v68
	ds_bpermute_b32 v69, v198, v69
	ds_bpermute_b32 v70, v198, v70
	ds_bpermute_b32 v71, v198, v71
	ds_bpermute_b32 v64, v198, v64
	ds_bpermute_b32 v65, v198, v65
	ds_bpermute_b32 v66, v198, v66
	ds_bpermute_b32 v67, v198, v67
	ds_bpermute_b32 v60, v198, v60
	ds_bpermute_b32 v61, v198, v61
	ds_bpermute_b32 v62, v198, v62
	ds_bpermute_b32 v63, v198, v63
	ds_bpermute_b32 v56, v198, v56
	ds_bpermute_b32 v57, v198, v57
	ds_bpermute_b32 v58, v198, v58
	ds_bpermute_b32 v59, v198, v59
	s_waitcnt vmcnt(36)
	s_waitcnt lgkmcnt(0)
	v_pk_fma_f32 v[132:133], v[68:69], v[148:149], v[132:133]
	v_pk_fma_f32 v[134:135], v[70:71], v[150:151], v[134:135]
	v_pk_fma_f32 v[128:129], v[64:65], v[144:145], v[128:129]
	v_pk_fma_f32 v[130:131], v[66:67], v[146:147], v[130:131]
	v_pk_fma_f32 v[124:125], v[60:61], v[140:141], v[124:125]
	v_pk_fma_f32 v[126:127], v[62:63], v[142:143], v[126:127]
	v_pk_fma_f32 v[120:121], v[56:57], v[136:137], v[120:121]
	v_pk_fma_f32 v[122:123], v[58:59], v[138:139], v[122:123]
	global_store_dwordx4 v[218:219], v[132:135], off nt
	global_store_dwordx4 v[218:219], v[128:131], off offset:64 nt
	global_store_dwordx4 v[218:219], v[124:127], off offset:512 nt
	global_store_dwordx4 v[218:219], v[120:123], off offset:576 nt
	v_cvt_pk_bf16_f32 v68, v132, v133
	v_cvt_pk_bf16_f32 v69, v134, v135
	v_cvt_pk_bf16_f32 v64, v128, v129
	v_cvt_pk_bf16_f32 v65, v130, v131
	v_cvt_pk_bf16_f32 v60, v124, v125
	v_cvt_pk_bf16_f32 v61, v126, v127
	v_cvt_pk_bf16_f32 v56, v120, v121
	v_cvt_pk_bf16_f32 v57, v122, v123
	global_store_dwordx2 v[242:243], v[68:69], off
	global_store_dwordx2 v[242:243], v[64:65], off offset:32
	global_store_dwordx2 v[242:243], v[60:61], off offset:256
	global_store_dwordx2 v[242:243], v[56:57], off offset:288
	s_mov_b32 s0, 0x10000
	s_mov_b32 s1, 0
	v_lshl_add_u64 v[218:219], v[218:219], 0, s[0:1]
	s_mov_b32 s0, 0x8000
	s_mov_b32 s1, 0
	v_lshl_add_u64 v[242:243], v[242:243], 0, s[0:1]
	ds_bpermute_b32 v52, v198, v52
	ds_bpermute_b32 v53, v198, v53
	ds_bpermute_b32 v54, v198, v54
	ds_bpermute_b32 v55, v198, v55
	ds_bpermute_b32 v48, v198, v48
	ds_bpermute_b32 v49, v198, v49
	ds_bpermute_b32 v50, v198, v50
	ds_bpermute_b32 v51, v198, v51
	ds_bpermute_b32 v44, v198, v44
	ds_bpermute_b32 v45, v198, v45
	ds_bpermute_b32 v46, v198, v46
	ds_bpermute_b32 v47, v198, v47
	ds_bpermute_b32 v40, v198, v40
	ds_bpermute_b32 v41, v198, v41
	ds_bpermute_b32 v42, v198, v42
	ds_bpermute_b32 v43, v198, v43
	s_waitcnt vmcnt(32)
	s_waitcnt lgkmcnt(0)
	v_pk_fma_f32 v[168:169], v[52:53], v[148:149], v[168:169]
	v_pk_fma_f32 v[170:171], v[54:55], v[150:151], v[170:171]
	v_pk_fma_f32 v[172:173], v[48:49], v[144:145], v[172:173]
	v_pk_fma_f32 v[174:175], v[50:51], v[146:147], v[174:175]
	v_pk_fma_f32 v[176:177], v[44:45], v[140:141], v[176:177]
	v_pk_fma_f32 v[178:179], v[46:47], v[142:143], v[178:179]
	v_pk_fma_f32 v[180:181], v[40:41], v[136:137], v[180:181]
	v_pk_fma_f32 v[182:183], v[42:43], v[138:139], v[182:183]
	global_store_dwordx4 v[218:219], v[168:171], off nt
	global_store_dwordx4 v[218:219], v[172:175], off offset:64 nt
	global_store_dwordx4 v[218:219], v[176:179], off offset:512 nt
	global_store_dwordx4 v[218:219], v[180:183], off offset:576 nt
	v_cvt_pk_bf16_f32 v52, v168, v169
	v_cvt_pk_bf16_f32 v53, v170, v171
	v_cvt_pk_bf16_f32 v48, v172, v173
	v_cvt_pk_bf16_f32 v49, v174, v175
	v_cvt_pk_bf16_f32 v44, v176, v177
	v_cvt_pk_bf16_f32 v45, v178, v179
	v_cvt_pk_bf16_f32 v40, v180, v181
	v_cvt_pk_bf16_f32 v41, v182, v183
	global_store_dwordx2 v[242:243], v[52:53], off
	global_store_dwordx2 v[242:243], v[48:49], off offset:32
	global_store_dwordx2 v[242:243], v[44:45], off offset:256
	global_store_dwordx2 v[242:243], v[40:41], off offset:288
	s_mov_b32 s0, 0x10000
	s_mov_b32 s1, 0
	v_lshl_add_u64 v[218:219], v[218:219], 0, s[0:1]
	s_mov_b32 s0, 0x8000
	s_mov_b32 s1, 0
	v_lshl_add_u64 v[242:243], v[242:243], 0, s[0:1]
	ds_bpermute_b32 v36, v198, v36
	ds_bpermute_b32 v37, v198, v37
	ds_bpermute_b32 v38, v198, v38
	ds_bpermute_b32 v39, v198, v39
	ds_bpermute_b32 v32, v198, v32
	ds_bpermute_b32 v33, v198, v33
	ds_bpermute_b32 v34, v198, v34
	ds_bpermute_b32 v35, v198, v35
	ds_bpermute_b32 v28, v198, v28
	ds_bpermute_b32 v29, v198, v29
	ds_bpermute_b32 v30, v198, v30
	ds_bpermute_b32 v31, v198, v31
	ds_bpermute_b32 v24, v198, v24
	ds_bpermute_b32 v25, v198, v25
	ds_bpermute_b32 v26, v198, v26
	ds_bpermute_b32 v27, v198, v27
	s_waitcnt vmcnt(36)
; __device__ __forceinline__ unsigned pk2(float lo, float hi) { const f32v2_t f = {lo, hi}; const bf16v2_t b = __builtin_convertvector(f, bf16v2_t); return __builtin_bit_cast(unsigned, b); }
;     __device__ __forceinline__ void operator()(const f32x4 (&acc)[2][2][4][2], const int upm, const int upn, const int usplit, int wr, int wc, int fr, int fq) const {
;     ...
; #pragma unroll
;         for (int ai = 0; ai < 2; ++ai)
; #pragma unroll
;             for (int mh = 0; mh < 2; ++mh) {
;                 f32x4 xv[2][2][2];
; #pragma unroll
;                 for (int m = 0; m < 2; ++m)
; #pragma unroll
;                     for (int bj = 0; bj < 2; ++bj)
; #pragma unroll
;                         for (int n = 0; n < 2; ++n) xv[m][bj][n] = *(const f32x4*)(sb + (size_t)(row0 + ai * HALF + (mh * 2 + m) * 16) * DM + col0 + bj * HALF + n * 16);
;                 __builtin_amdgcn_sched_barrier(0);
; #pragma unroll
;                 for (int m = 0; m < 2; ++m)
; #pragma unroll
;                     for (int bj = 0; bj < 2; ++bj)
; #pragma unroll
;                         for (int n = 0; n < 2; ++n) {
;                             const size_t o = (size_t)(row0 + ai * HALF + (mh * 2 + m) * 16) * DM + col0 + bj * HALF + n * 16;
;                             const f32x4 r = xv[m][bj][n] + gv[bj][n] * acc[ai][bj][mh * 2 + m][n];
;                             *(f32x4*)(db + o) = r;
;                             if (xb && lat) { u32x2 pk; pk.x = pk2(r[0], r[1]); pk.y = pk2(r[2], r[3]); *(u32x2*)(xb + o) = pk; }
;                         }
	s_waitcnt lgkmcnt(0)
	v_pk_fma_f32 v[116:117], v[36:37], v[148:149], v[116:117]
	v_pk_fma_f32 v[118:119], v[38:39], v[150:151], v[118:119]
	v_pk_fma_f32 v[112:113], v[32:33], v[144:145], v[112:113]
	v_pk_fma_f32 v[114:115], v[34:35], v[146:147], v[114:115]
	v_pk_fma_f32 v[108:109], v[28:29], v[140:141], v[108:109]
	v_pk_fma_f32 v[110:111], v[30:31], v[142:143], v[110:111]
	v_pk_fma_f32 v[104:105], v[24:25], v[136:137], v[104:105]
	v_pk_fma_f32 v[106:107], v[26:27], v[138:139], v[106:107]
	global_store_dwordx4 v[218:219], v[116:119], off nt
	global_store_dwordx4 v[218:219], v[112:115], off offset:64 nt
	global_store_dwordx4 v[218:219], v[108:111], off offset:512 nt
	global_store_dwordx4 v[218:219], v[104:107], off offset:576 nt
	v_cvt_pk_bf16_f32 v36, v116, v117
	v_cvt_pk_bf16_f32 v37, v118, v119
	v_cvt_pk_bf16_f32 v32, v112, v113
	v_cvt_pk_bf16_f32 v33, v114, v115
	v_cvt_pk_bf16_f32 v28, v108, v109
	v_cvt_pk_bf16_f32 v29, v110, v111
	v_cvt_pk_bf16_f32 v24, v104, v105
	v_cvt_pk_bf16_f32 v25, v106, v107
	global_store_dwordx2 v[242:243], v[36:37], off
	global_store_dwordx2 v[242:243], v[32:33], off offset:32
	global_store_dwordx2 v[242:243], v[28:29], off offset:256
	global_store_dwordx2 v[242:243], v[24:25], off offset:288
	s_mov_b32 s0, 0x10000
	s_mov_b32 s1, 0
	v_lshl_add_u64 v[218:219], v[218:219], 0, s[0:1]
	s_mov_b32 s0, 0x8000
	s_mov_b32 s1, 0
	v_lshl_add_u64 v[242:243], v[242:243], 0, s[0:1]
	ds_bpermute_b32 v20, v198, v20
	ds_bpermute_b32 v21, v198, v21
	ds_bpermute_b32 v22, v198, v22
	ds_bpermute_b32 v23, v198, v23
	ds_bpermute_b32 v16, v198, v16
	ds_bpermute_b32 v17, v198, v17
	ds_bpermute_b32 v18, v198, v18
	ds_bpermute_b32 v19, v198, v19
	ds_bpermute_b32 v12, v198, v12
	ds_bpermute_b32 v13, v198, v13
	ds_bpermute_b32 v14, v198, v14
	ds_bpermute_b32 v15, v198, v15
	ds_bpermute_b32 v8, v198, v8
	ds_bpermute_b32 v9, v198, v9
	ds_bpermute_b32 v10, v198, v10
	ds_bpermute_b32 v11, v198, v11
	s_waitcnt vmcnt(32)
	s_waitcnt lgkmcnt(0)
	v_pk_fma_f32 v[190:191], v[20:21], v[148:149], v[190:191]
	v_pk_fma_f32 v[192:193], v[22:23], v[150:151], v[192:193]
	v_pk_fma_f32 v[194:195], v[16:17], v[144:145], v[194:195]
	v_pk_fma_f32 v[196:197], v[18:19], v[146:147], v[196:197]
	v_pk_fma_f32 v[234:235], v[12:13], v[140:141], v[234:235]
	v_pk_fma_f32 v[236:237], v[14:15], v[142:143], v[236:237]
	v_pk_fma_f32 v[238:239], v[8:9], v[136:137], v[238:239]
	v_pk_fma_f32 v[240:241], v[10:11], v[138:139], v[240:241]
	global_store_dwordx4 v[218:219], v[190:193], off nt
	global_store_dwordx4 v[218:219], v[194:197], off offset:64 nt
	global_store_dwordx4 v[218:219], v[234:237], off offset:512 nt
	global_store_dwordx4 v[218:219], v[238:241], off offset:576 nt
	v_cvt_pk_bf16_f32 v20, v190, v191
	v_cvt_pk_bf16_f32 v21, v192, v193
	v_cvt_pk_bf16_f32 v16, v194, v195
	v_cvt_pk_bf16_f32 v17, v196, v197
	v_cvt_pk_bf16_f32 v12, v234, v235
	v_cvt_pk_bf16_f32 v13, v236, v237
	v_cvt_pk_bf16_f32 v8, v238, v239
	v_cvt_pk_bf16_f32 v9, v240, v241
	global_store_dwordx2 v[242:243], v[20:21], off
	global_store_dwordx2 v[242:243], v[16:17], off offset:32
	global_store_dwordx2 v[242:243], v[12:13], off offset:256
	global_store_dwordx2 v[242:243], v[8:9], off offset:288
	s_branch .LBB0_1846
.Lmy_epi_p7_nobf:
	ds_bpermute_b32 v132, v198, v132
	ds_bpermute_b32 v133, v198, v133
	ds_bpermute_b32 v134, v198, v134
	ds_bpermute_b32 v135, v198, v135
	ds_bpermute_b32 v128, v198, v128
	ds_bpermute_b32 v129, v198, v129
	ds_bpermute_b32 v130, v198, v130
	ds_bpermute_b32 v131, v198, v131
	ds_bpermute_b32 v124, v198, v124
	ds_bpermute_b32 v125, v198, v125
	ds_bpermute_b32 v126, v198, v126
	ds_bpermute_b32 v127, v198, v127
	ds_bpermute_b32 v120, v198, v120
	ds_bpermute_b32 v121, v198, v121
	ds_bpermute_b32 v122, v198, v122
	ds_bpermute_b32 v123, v198, v123
	s_waitcnt vmcnt(8)
	s_waitcnt lgkmcnt(0)
	v_pk_fma_f32 v[152:153], v[132:133], v[148:149], v[152:153]
	v_pk_fma_f32 v[154:155], v[134:135], v[150:151], v[154:155]
	v_pk_fma_f32 v[156:157], v[128:129], v[144:145], v[156:157]
	v_pk_fma_f32 v[158:159], v[130:131], v[146:147], v[158:159]
	v_pk_fma_f32 v[160:161], v[124:125], v[140:141], v[160:161]
	v_pk_fma_f32 v[162:163], v[126:127], v[142:143], v[162:163]
	v_pk_fma_f32 v[164:165], v[120:121], v[136:137], v[164:165]
	v_pk_fma_f32 v[166:167], v[122:123], v[138:139], v[166:167]
	global_store_dwordx4 v[218:219], v[152:155], off nt
	global_store_dwordx4 v[218:219], v[156:159], off offset:64 nt
	global_store_dwordx4 v[218:219], v[160:163], off offset:512 nt
	global_store_dwordx4 v[218:219], v[164:167], off offset:576 nt
	s_mov_b32 s0, 0x10000
	s_mov_b32 s1, 0
	v_lshl_add_u64 v[218:219], v[218:219], 0, s[0:1]
	global_load_dwordx4 v[152:155], v[200:201], off nt
	global_load_dwordx4 v[156:159], v[200:201], off offset:64 nt
	global_load_dwordx4 v[160:163], v[200:201], off offset:512 nt
	global_load_dwordx4 v[164:167], v[200:201], off offset:576 nt
	s_mov_b32 s0, 0x50000
	s_mov_b32 s1, 0
	v_lshl_add_u64 v[200:201], v[200:201], 0, s[0:1]
	global_load_dwordx4 v[132:135], v[200:201], off nt
	global_load_dwordx4 v[128:131], v[200:201], off offset:64 nt
	global_load_dwordx4 v[124:127], v[200:201], off offset:512 nt
	global_load_dwordx4 v[120:123], v[200:201], off offset:576 nt
	s_mov_b32 s0, 0x10000
	s_mov_b32 s1, 0
	v_lshl_add_u64 v[200:201], v[200:201], 0, s[0:1]
	ds_bpermute_b32 v116, v198, v116
	ds_bpermute_b32 v117, v198, v117
	ds_bpermute_b32 v118, v198, v118
	ds_bpermute_b32 v119, v198, v119
	ds_bpermute_b32 v112, v198, v112
	ds_bpermute_b32 v113, v198, v113
	ds_bpermute_b32 v114, v198, v114
	ds_bpermute_b32 v115, v198, v115
	ds_bpermute_b32 v108, v198, v108
	ds_bpermute_b32 v109, v198, v109
	ds_bpermute_b32 v110, v198, v110
	ds_bpermute_b32 v111, v198, v111
	ds_bpermute_b32 v104, v198, v104
	ds_bpermute_b32 v105, v198, v105
	ds_bpermute_b32 v106, v198, v106
	ds_bpermute_b32 v107, v198, v107
	s_waitcnt vmcnt(16)
; __device__ __forceinline__ unsigned pk2(float lo, float hi) { const f32v2_t f = {lo, hi}; const bf16v2_t b = __builtin_convertvector(f, bf16v2_t); return __builtin_bit_cast(unsigned, b); }
;     __device__ __forceinline__ void operator()(const f32x4 (&acc)[2][2][4][2], const int upm, const int upn, const int usplit, int wr, int wc, int fr, int fq) const {
;     ...
; #pragma unroll
;         for (int ai = 0; ai < 2; ++ai)
; #pragma unroll
;             for (int mh = 0; mh < 2; ++mh) {
;                 f32x4 xv[2][2][2];
; #pragma unroll
;                 for (int m = 0; m < 2; ++m)
; #pragma unroll
;                     for (int bj = 0; bj < 2; ++bj)
; #pragma unroll
;                         for (int n = 0; n < 2; ++n) xv[m][bj][n] = *(const f32x4*)(sb + (size_t)(row0 + ai * HALF + (mh * 2 + m) * 16) * DM + col0 + bj * HALF + n * 16);
;                 __builtin_amdgcn_sched_barrier(0);
; #pragma unroll
;                 for (int m = 0; m < 2; ++m)
; #pragma unroll
;                     for (int bj = 0; bj < 2; ++bj)
; #pragma unroll
;                         for (int n = 0; n < 2; ++n) {
;                             const size_t o = (size_t)(row0 + ai * HALF + (mh * 2 + m) * 16) * DM + col0 + bj * HALF + n * 16;
;                             const f32x4 r = xv[m][bj][n] + gv[bj][n] * acc[ai][bj][mh * 2 + m][n];
;                             *(f32x4*)(db + o) = r;
;                             if (xb && lat) { u32x2 pk; pk.x = pk2(r[0], r[1]); pk.y = pk2(r[2], r[3]); *(u32x2*)(xb + o) = pk; }
;                         }
	s_waitcnt lgkmcnt(0)
	v_pk_fma_f32 v[168:169], v[116:117], v[148:149], v[168:169]
	v_pk_fma_f32 v[170:171], v[118:119], v[150:151], v[170:171]
	v_pk_fma_f32 v[172:173], v[112:113], v[144:145], v[172:173]
	v_pk_fma_f32 v[174:175], v[114:115], v[146:147], v[174:175]
	v_pk_fma_f32 v[176:177], v[108:109], v[140:141], v[176:177]
	v_pk_fma_f32 v[178:179], v[110:111], v[142:143], v[178:179]
	v_pk_fma_f32 v[180:181], v[104:105], v[136:137], v[180:181]
	v_pk_fma_f32 v[182:183], v[106:107], v[138:139], v[182:183]
	global_store_dwordx4 v[218:219], v[168:171], off nt
	global_store_dwordx4 v[218:219], v[172:175], off offset:64 nt
	global_store_dwordx4 v[218:219], v[176:179], off offset:512 nt
	global_store_dwordx4 v[218:219], v[180:183], off offset:576 nt
	s_mov_b32 s0, 0x10000
	s_mov_b32 s1, 0
	v_lshl_add_u64 v[218:219], v[218:219], 0, s[0:1]
	global_load_dwordx4 v[168:171], v[200:201], off nt
	global_load_dwordx4 v[172:175], v[200:201], off offset:64 nt
	global_load_dwordx4 v[176:179], v[200:201], off offset:512 nt
	global_load_dwordx4 v[180:183], v[200:201], off offset:576 nt
	s_mov_b32 s0, 0x10000
	s_mov_b32 s1, 0
	v_lshl_add_u64 v[200:201], v[200:201], 0, s[0:1]
	global_load_dwordx4 v[116:119], v[200:201], off nt
	global_load_dwordx4 v[112:115], v[200:201], off offset:64 nt
	global_load_dwordx4 v[108:111], v[200:201], off offset:512 nt
	global_load_dwordx4 v[104:107], v[200:201], off offset:576 nt
	s_mov_b32 s0, 0x10000
	s_mov_b32 s1, 0
	v_lshl_add_u64 v[200:201], v[200:201], 0, s[0:1]
	ds_bpermute_b32 v100, v198, v100
	ds_bpermute_b32 v101, v198, v101
	ds_bpermute_b32 v102, v198, v102
	ds_bpermute_b32 v103, v198, v103
	ds_bpermute_b32 v96, v198, v96
	ds_bpermute_b32 v97, v198, v97
	ds_bpermute_b32 v98, v198, v98
	ds_bpermute_b32 v99, v198, v99
	ds_bpermute_b32 v92, v198, v92
	ds_bpermute_b32 v93, v198, v93
	ds_bpermute_b32 v94, v198, v94
	ds_bpermute_b32 v95, v198, v95
	ds_bpermute_b32 v88, v198, v88
	ds_bpermute_b32 v89, v198, v89
	ds_bpermute_b32 v90, v198, v90
	ds_bpermute_b32 v91, v198, v91
	s_waitcnt vmcnt(24)
	s_waitcnt lgkmcnt(0)
	v_pk_fma_f32 v[190:191], v[100:101], v[148:149], v[190:191]
	v_pk_fma_f32 v[192:193], v[102:103], v[150:151], v[192:193]
	v_pk_fma_f32 v[194:195], v[96:97], v[144:145], v[194:195]
	v_pk_fma_f32 v[196:197], v[98:99], v[146:147], v[196:197]
	v_pk_fma_f32 v[234:235], v[92:93], v[140:141], v[234:235]
	v_pk_fma_f32 v[236:237], v[94:95], v[142:143], v[236:237]
	v_pk_fma_f32 v[238:239], v[88:89], v[136:137], v[238:239]
	v_pk_fma_f32 v[240:241], v[90:91], v[138:139], v[240:241]
	global_store_dwordx4 v[218:219], v[190:193], off nt
	global_store_dwordx4 v[218:219], v[194:197], off offset:64 nt
	global_store_dwordx4 v[218:219], v[234:237], off offset:512 nt
	global_store_dwordx4 v[218:219], v[238:241], off offset:576 nt
	s_mov_b32 s0, 0x10000
	s_mov_b32 s1, 0
	v_lshl_add_u64 v[218:219], v[218:219], 0, s[0:1]
	global_load_dwordx4 v[190:193], v[200:201], off nt
	global_load_dwordx4 v[194:197], v[200:201], off offset:64 nt
	global_load_dwordx4 v[234:237], v[200:201], off offset:512 nt
	global_load_dwordx4 v[238:241], v[200:201], off offset:576 nt
	ds_bpermute_b32 v84, v198, v84
	ds_bpermute_b32 v85, v198, v85
	ds_bpermute_b32 v86, v198, v86
	ds_bpermute_b32 v87, v198, v87
	ds_bpermute_b32 v80, v198, v80
	ds_bpermute_b32 v81, v198, v81
	ds_bpermute_b32 v82, v198, v82
	ds_bpermute_b32 v83, v198, v83
	ds_bpermute_b32 v76, v198, v76
	ds_bpermute_b32 v77, v198, v77
	ds_bpermute_b32 v78, v198, v78
	ds_bpermute_b32 v79, v198, v79
	ds_bpermute_b32 v72, v198, v72
	ds_bpermute_b32 v73, v198, v73
	ds_bpermute_b32 v74, v198, v74
	ds_bpermute_b32 v75, v198, v75
	s_waitcnt vmcnt(24)
	s_waitcnt lgkmcnt(0)
	v_pk_fma_f32 v[152:153], v[84:85], v[148:149], v[152:153]
	v_pk_fma_f32 v[154:155], v[86:87], v[150:151], v[154:155]
	v_pk_fma_f32 v[156:157], v[80:81], v[144:145], v[156:157]
	v_pk_fma_f32 v[158:159], v[82:83], v[146:147], v[158:159]
	v_pk_fma_f32 v[160:161], v[76:77], v[140:141], v[160:161]
	v_pk_fma_f32 v[162:163], v[78:79], v[142:143], v[162:163]
	v_pk_fma_f32 v[164:165], v[72:73], v[136:137], v[164:165]
	v_pk_fma_f32 v[166:167], v[74:75], v[138:139], v[166:167]
	global_store_dwordx4 v[218:219], v[152:155], off nt
	global_store_dwordx4 v[218:219], v[156:159], off offset:64 nt
	global_store_dwordx4 v[218:219], v[160:163], off offset:512 nt
	global_store_dwordx4 v[218:219], v[164:167], off offset:576 nt
	s_mov_b32 s0, 0x50000
	s_mov_b32 s1, 0
	v_lshl_add_u64 v[218:219], v[218:219], 0, s[0:1]
	ds_bpermute_b32 v68, v198, v68
	ds_bpermute_b32 v69, v198, v69
	ds_bpermute_b32 v70, v198, v70
	ds_bpermute_b32 v71, v198, v71
	ds_bpermute_b32 v64, v198, v64
	ds_bpermute_b32 v65, v198, v65
	ds_bpermute_b32 v66, v198, v66
	ds_bpermute_b32 v67, v198, v67
	ds_bpermute_b32 v60, v198, v60
	ds_bpermute_b32 v61, v198, v61
	ds_bpermute_b32 v62, v198, v62
	ds_bpermute_b32 v63, v198, v63
	ds_bpermute_b32 v56, v198, v56
	ds_bpermute_b32 v57, v198, v57
	ds_bpermute_b32 v58, v198, v58
	ds_bpermute_b32 v59, v198, v59
	s_waitcnt vmcnt(24)
; __device__ __forceinline__ unsigned pk2(float lo, float hi) { const f32v2_t f = {lo, hi}; const bf16v2_t b = __builtin_convertvector(f, bf16v2_t); return __builtin_bit_cast(unsigned, b); }
;     __device__ __forceinline__ void operator()(const f32x4 (&acc)[2][2][4][2], const int upm, const int upn, const int usplit, int wr, int wc, int fr, int fq) const {
;     ...
; #pragma unroll
;         for (int ai = 0; ai < 2; ++ai)
; #pragma unroll
;             for (int mh = 0; mh < 2; ++mh) {
;                 f32x4 xv[2][2][2];
; #pragma unroll
;                 for (int m = 0; m < 2; ++m)
; #pragma unroll
;                     for (int bj = 0; bj < 2; ++bj)
; #pragma unroll
;                         for (int n = 0; n < 2; ++n) xv[m][bj][n] = *(const f32x4*)(sb + (size_t)(row0 + ai * HALF + (mh * 2 + m) * 16) * DM + col0 + bj * HALF + n * 16);
;                 __builtin_amdgcn_sched_barrier(0);
; #pragma unroll
;                 for (int m = 0; m < 2; ++m)
; #pragma unroll
;                     for (int bj = 0; bj < 2; ++bj)
; #pragma unroll
;                         for (int n = 0; n < 2; ++n) {
;                             const size_t o = (size_t)(row0 + ai * HALF + (mh * 2 + m) * 16) * DM + col0 + bj * HALF + n * 16;
;                             const f32x4 r = xv[m][bj][n] + gv[bj][n] * acc[ai][bj][mh * 2 + m][n];
;                             *(f32x4*)(db + o) = r;
;                             if (xb && lat) { u32x2 pk; pk.x = pk2(r[0], r[1]); pk.y = pk2(r[2], r[3]); *(u32x2*)(xb + o) = pk; }
;                         }
	s_waitcnt lgkmcnt(0)
	v_pk_fma_f32 v[132:133], v[68:69], v[148:149], v[132:133]
	v_pk_fma_f32 v[134:135], v[70:71], v[150:151], v[134:135]
	v_pk_fma_f32 v[128:129], v[64:65], v[144:145], v[128:129]
	v_pk_fma_f32 v[130:131], v[66:67], v[146:147], v[130:131]
	v_pk_fma_f32 v[124:125], v[60:61], v[140:141], v[124:125]
	v_pk_fma_f32 v[126:127], v[62:63], v[142:143], v[126:127]
	v_pk_fma_f32 v[120:121], v[56:57], v[136:137], v[120:121]
	v_pk_fma_f32 v[122:123], v[58:59], v[138:139], v[122:123]
	global_store_dwordx4 v[218:219], v[132:135], off nt
	global_store_dwordx4 v[218:219], v[128:131], off offset:64 nt
	global_store_dwordx4 v[218:219], v[124:127], off offset:512 nt
	global_store_dwordx4 v[218:219], v[120:123], off offset:576 nt
	s_mov_b32 s0, 0x10000
	s_mov_b32 s1, 0
	v_lshl_add_u64 v[218:219], v[218:219], 0, s[0:1]
	ds_bpermute_b32 v52, v198, v52
	ds_bpermute_b32 v53, v198, v53
	ds_bpermute_b32 v54, v198, v54
	ds_bpermute_b32 v55, v198, v55
	ds_bpermute_b32 v48, v198, v48
	ds_bpermute_b32 v49, v198, v49
	ds_bpermute_b32 v50, v198, v50
	ds_bpermute_b32 v51, v198, v51
	ds_bpermute_b32 v44, v198, v44
	ds_bpermute_b32 v45, v198, v45
	ds_bpermute_b32 v46, v198, v46
	ds_bpermute_b32 v47, v198, v47
	ds_bpermute_b32 v40, v198, v40
	ds_bpermute_b32 v41, v198, v41
	ds_bpermute_b32 v42, v198, v42
	ds_bpermute_b32 v43, v198, v43
	s_waitcnt vmcnt(20)
	s_waitcnt lgkmcnt(0)
	v_pk_fma_f32 v[168:169], v[52:53], v[148:149], v[168:169]
	v_pk_fma_f32 v[170:171], v[54:55], v[150:151], v[170:171]
	v_pk_fma_f32 v[172:173], v[48:49], v[144:145], v[172:173]
	v_pk_fma_f32 v[174:175], v[50:51], v[146:147], v[174:175]
	v_pk_fma_f32 v[176:177], v[44:45], v[140:141], v[176:177]
	v_pk_fma_f32 v[178:179], v[46:47], v[142:143], v[178:179]
	v_pk_fma_f32 v[180:181], v[40:41], v[136:137], v[180:181]
	v_pk_fma_f32 v[182:183], v[42:43], v[138:139], v[182:183]
	global_store_dwordx4 v[218:219], v[168:171], off nt
	global_store_dwordx4 v[218:219], v[172:175], off offset:64 nt
	global_store_dwordx4 v[218:219], v[176:179], off offset:512 nt
	global_store_dwordx4 v[218:219], v[180:183], off offset:576 nt
	s_mov_b32 s0, 0x10000
	s_mov_b32 s1, 0
	v_lshl_add_u64 v[218:219], v[218:219], 0, s[0:1]
	ds_bpermute_b32 v36, v198, v36
	ds_bpermute_b32 v37, v198, v37
	ds_bpermute_b32 v38, v198, v38
	ds_bpermute_b32 v39, v198, v39
	ds_bpermute_b32 v32, v198, v32
	ds_bpermute_b32 v33, v198, v33
	ds_bpermute_b32 v34, v198, v34
	ds_bpermute_b32 v35, v198, v35
	ds_bpermute_b32 v28, v198, v28
	ds_bpermute_b32 v29, v198, v29
	ds_bpermute_b32 v30, v198, v30
	ds_bpermute_b32 v31, v198, v31
	ds_bpermute_b32 v24, v198, v24
	ds_bpermute_b32 v25, v198, v25
	ds_bpermute_b32 v26, v198, v26
	ds_bpermute_b32 v27, v198, v27
	s_waitcnt vmcnt(20)
	s_waitcnt lgkmcnt(0)
	v_pk_fma_f32 v[116:117], v[36:37], v[148:149], v[116:117]
	v_pk_fma_f32 v[118:119], v[38:39], v[150:151], v[118:119]
	v_pk_fma_f32 v[112:113], v[32:33], v[144:145], v[112:113]
	v_pk_fma_f32 v[114:115], v[34:35], v[146:147], v[114:115]
	v_pk_fma_f32 v[108:109], v[28:29], v[140:141], v[108:109]
	v_pk_fma_f32 v[110:111], v[30:31], v[142:143], v[110:111]
	v_pk_fma_f32 v[104:105], v[24:25], v[136:137], v[104:105]
	v_pk_fma_f32 v[106:107], v[26:27], v[138:139], v[106:107]
	global_store_dwordx4 v[218:219], v[116:119], off nt
	global_store_dwordx4 v[218:219], v[112:115], off offset:64 nt
	global_store_dwordx4 v[218:219], v[108:111], off offset:512 nt
	global_store_dwordx4 v[218:219], v[104:107], off offset:576 nt
	s_mov_b32 s0, 0x10000
	s_mov_b32 s1, 0
	v_lshl_add_u64 v[218:219], v[218:219], 0, s[0:1]
	ds_bpermute_b32 v20, v198, v20
	ds_bpermute_b32 v21, v198, v21
	ds_bpermute_b32 v22, v198, v22
	ds_bpermute_b32 v23, v198, v23
	ds_bpermute_b32 v16, v198, v16
	ds_bpermute_b32 v17, v198, v17
	ds_bpermute_b32 v18, v198, v18
	ds_bpermute_b32 v19, v198, v19
	ds_bpermute_b32 v12, v198, v12
	ds_bpermute_b32 v13, v198, v13
	ds_bpermute_b32 v14, v198, v14
	ds_bpermute_b32 v15, v198, v15
	ds_bpermute_b32 v8, v198, v8
	ds_bpermute_b32 v9, v198, v9
	ds_bpermute_b32 v10, v198, v10
	ds_bpermute_b32 v11, v198, v11
	s_waitcnt vmcnt(16)
	s_waitcnt lgkmcnt(0)
	v_pk_fma_f32 v[190:191], v[20:21], v[148:149], v[190:191]
	v_pk_fma_f32 v[192:193], v[22:23], v[150:151], v[192:193]
	v_pk_fma_f32 v[194:195], v[16:17], v[144:145], v[194:195]
	v_pk_fma_f32 v[196:197], v[18:19], v[146:147], v[196:197]
	v_pk_fma_f32 v[234:235], v[12:13], v[140:141], v[234:235]
	v_pk_fma_f32 v[236:237], v[14:15], v[142:143], v[236:237]
	v_pk_fma_f32 v[238:239], v[8:9], v[136:137], v[238:239]
	v_pk_fma_f32 v[240:241], v[10:11], v[138:139], v[240:241]
	global_store_dwordx4 v[218:219], v[190:193], off nt
	global_store_dwordx4 v[218:219], v[194:197], off offset:64 nt
	global_store_dwordx4 v[218:219], v[234:237], off offset:512 nt
	global_store_dwordx4 v[218:219], v[238:241], off offset:576 nt
	s_branch .LBB0_1846
